# EpiUp: g-tile DMA wait split by tile half (upper-half conv/silu runs while rows 144..255 are still landing), edge rows issued first
# baseline (speedup 1.0000x reference)
.LBB0_37:
	s_or_b64 exec, exec, s[0:1]
	v_readlane_b32 s50, v253, 47
	v_readlane_b32 s51, v253, 48
	v_and_b32_e32 v126, 63, v206
	v_lshrrev_b32_e32 v127, 6, v206
	v_and_b32_e32 v128, 15, v206
	v_bfe_u32 v129, v206, 4, 2
	v_and_b32_e32 v130, 3, v127
	v_lshrrev_b32_e32 v131, 2, v127
	v_readfirstlane_b32 s0, v127
	s_mul_i32 s1, s10, 0x2c00
	s_lshl_b32 s5, s4, 1
	s_add_u32 s12, s50, s1
	s_addc_u32 s13, s51, 0
	s_add_u32 s12, s12, s5
	s_addc_u32 s13, s13, 0
	s_sub_u32 s36, s12, 0x2c00
	s_subb_u32 s37, s13, 0
	s_add_u32 s14, s20, s1
	s_addc_u32 s15, s21, 0
	s_add_u32 s14, s14, s5
	s_addc_u32 s15, s15, 0
	s_lshl_b32 s5, s4, 2
	s_add_u32 s16, s8, s5
	s_addc_u32 s17, s9, 0
	s_add_u32 s52, s16, 0x5800
	s_addc_u32 s53, s17, 0
	s_add_u32 s56, s16, 0xb000
	s_addc_u32 s57, s17, 0
	s_sub_u32 s1, s10, 0x1000
	s_and_b32 s1, s1, 0x7ff
	s_cmp_eq_u32 s1, 0
	s_cselect_b32 s62, 1, 0
	s_cmp_eq_u32 s1, 0x700
	s_cselect_b32 s63, 1, 0
	s_cmp_lt_u32 s10, 0x1000
	s_cselect_b32 s62, 1, s62
	s_cselect_b32 s63, 1, s63
	v_lshlrev_b32_e32 v136, 5, v130
	v_lshl_add_u32 v136, v129, 2, v136
	v_lshlrev_b32_e32 v137, 2, v136
	global_load_dwordx4 v[142:145], v137, s[16:17]
	global_load_dwordx4 v[146:149], v137, s[52:53]
	global_load_dwordx4 v[150:153], v137, s[56:57]
	global_load_dwordx4 v[154:157], v137, s[16:17] offset:64
	global_load_dwordx4 v[158:161], v137, s[52:53] offset:64
	global_load_dwordx4 v[162:165], v137, s[56:57] offset:64
	global_load_dwordx4 v[166:169], v137, s[16:17] offset:512
	global_load_dwordx4 v[170:173], v137, s[52:53] offset:512
	global_load_dwordx4 v[174:177], v137, s[56:57] offset:512
	global_load_dwordx4 v[178:181], v137, s[16:17] offset:576
	global_load_dwordx4 v[182:185], v137, s[52:53] offset:576
	global_load_dwordx4 v[186:189], v137, s[56:57] offset:576
	s_cmp_lg_u32 s0, 0
	s_cbranch_scc1 .Lepiup_noextra
	v_cmp_gt_u32_e32 vcc, 32, v126
	v_and_b32_e32 v134, 31, v126
	v_xor_b32_e32 v133, 15, v134
	v_lshlrev_b32_e32 v133, 4, v133
	v_lshlrev_b32_e32 v134, 4, v134
	v_add_u32_e32 v134, 0x2c2c00, v134
	v_cndmask_b32_e32 v133, v134, v133, vcc
	v_lshlrev_b32_e32 v134, 4, v126
	v_add_u32_e32 v134, 0x20100, v134
	v_mov_b32_e32 v0, 0
	v_mov_b32_e32 v132, 0
	s_cmp_lg_u32 s62, 0
	s_cselect_b32 s38, -1, 0
	s_cmp_lg_u32 s63, 0
	s_cselect_b32 s39, -1, 0
	s_mov_b64 s[40:41], exec
	s_mov_b64 exec, s[38:39]
	s_cbranch_execz .Lepiup_nozero
	ds_write_b64 v134, v[0:1]
	ds_write_b64 v134, v[0:1] offset:8

.Lepiup_noextra:
	v_lshrrev_b32_e32 v132, 5, v126
	v_lshl_add_u32 v133, v127, 1, v132
	v_and_b32_e32 v134, 31, v126
	v_xor_b32_e32 v134, v134, v133
	v_mul_u32_u24_e32 v135, 0x2c00, v133
	v_lshl_add_u32 v135, v134, 4, v135
	s_lshl_b32 s1, s0, 10
	s_mov_b32 m0, s1
	s_add_i32 s1, s1, 0x2000
	global_load_lds_dwordx4 v135, s[12:13]
	s_add_u32 s12, s12, 0x2c000
	s_addc_u32 s13, s13, 0
	s_mov_b32 m0, s1
	s_add_i32 s1, s1, 0x2000
	global_load_lds_dwordx4 v135, s[12:13]
	s_add_u32 s12, s12, 0x2c000
	s_addc_u32 s13, s13, 0
	s_mov_b32 m0, s1
	s_add_i32 s1, s1, 0x2000
	global_load_lds_dwordx4 v135, s[12:13]
	s_add_u32 s12, s12, 0x2c000
	s_addc_u32 s13, s13, 0
	s_mov_b32 m0, s1
	s_add_i32 s1, s1, 0x2000
	global_load_lds_dwordx4 v135, s[12:13]
	s_add_u32 s12, s12, 0x2c000
	s_addc_u32 s13, s13, 0
	s_mov_b32 m0, s1
	s_add_i32 s1, s1, 0x2000
	global_load_lds_dwordx4 v135, s[12:13]
	s_add_u32 s12, s12, 0x2c000
	s_addc_u32 s13, s13, 0
	s_mov_b32 m0, s1
	s_add_i32 s1, s1, 0x2000
	global_load_lds_dwordx4 v135, s[12:13]
	s_add_u32 s12, s12, 0x2c000
	s_addc_u32 s13, s13, 0
	s_mov_b32 m0, s1
	s_add_i32 s1, s1, 0x2000
	global_load_lds_dwordx4 v135, s[12:13]
	s_add_u32 s12, s12, 0x2c000
	s_addc_u32 s13, s13, 0
	s_mov_b32 m0, s1
	s_add_i32 s1, s1, 0x2000
	global_load_lds_dwordx4 v135, s[12:13]
	s_add_u32 s12, s12, 0x2c000
	s_addc_u32 s13, s13, 0
	s_mov_b32 m0, s1
	s_add_i32 s1, s1, 0x2000
	global_load_lds_dwordx4 v135, s[12:13]
	s_add_u32 s12, s12, 0x2c000
	s_addc_u32 s13, s13, 0
	s_mov_b32 m0, s1
	s_add_i32 s1, s1, 0x2000
	global_load_lds_dwordx4 v135, s[12:13]
	s_add_u32 s12, s12, 0x2c000
	s_addc_u32 s13, s13, 0
	s_mov_b32 m0, s1
	s_add_i32 s1, s1, 0x2000
	global_load_lds_dwordx4 v135, s[12:13]
	s_add_u32 s12, s12, 0x2c000
	s_addc_u32 s13, s13, 0
	s_mov_b32 m0, s1
	s_add_i32 s1, s1, 0x2000
	global_load_lds_dwordx4 v135, s[12:13]
	s_add_u32 s12, s12, 0x2c000
	s_addc_u32 s13, s13, 0
	s_mov_b32 m0, s1
	s_add_i32 s1, s1, 0x2000
	global_load_lds_dwordx4 v135, s[12:13]
	s_add_u32 s12, s12, 0x2c000
	s_addc_u32 s13, s13, 0
	s_mov_b32 m0, s1
	s_add_i32 s1, s1, 0x2000
	global_load_lds_dwordx4 v135, s[12:13]
	s_add_u32 s12, s12, 0x2c000
	s_addc_u32 s13, s13, 0
	s_mov_b32 m0, s1
	s_add_i32 s1, s1, 0x2000
	global_load_lds_dwordx4 v135, s[12:13]
	s_add_u32 s12, s12, 0x2c000
	s_addc_u32 s13, s13, 0
	s_mov_b32 m0, s1
	s_add_i32 s1, s1, 0x2000
	global_load_lds_dwordx4 v135, s[12:13]
	v_lshrrev_b32_e32 v132, 1, v129
	v_lshl_add_u32 v132, v130, 2, v132
	v_and_b32_e32 v133, 1, v129
	v_lshlrev_b32_e32 v133, 3, v133
	v_lshl_add_u32 v134, v131, 6, v128
	v_add_u32_e32 v135, 15, v128
	v_and_b32_e32 v135, 15, v135
	v_add_u32_e32 v137, 1, v128
	v_and_b32_e32 v137, 15, v137
	v_cmp_eq_u32_e64 s[38:39], 0, v134
	s_movk_i32 s1, 0x4f
	v_cmp_eq_u32_e64 s[40:41], s1, v134
	v_mov_b32_e32 v244, v132
	v_xor_b32_e32 v245, v244, v135
	v_xor_b32_e32 v246, v244, v128
	v_xor_b32_e32 v247, v244, v137
	v_lshl_add_u32 v245, v245, 4, v133
	v_lshl_add_u32 v246, v246, 4, v133
	v_lshl_add_u32 v247, v247, 4, v133
	v_lshlrev_b32_e32 v248, 9, v134
	v_add_u32_e32 v194, v248, v246
	v_add_u32_e32 v249, 0x200, v248
	v_add_u32_e32 v196, v249, v247
	v_add_u32_e32 v249, 0x1e00, v248
	v_add_u32_e32 v190, v249, v245
	v_add_u32_e32 v249, 0xfe00, v248
	v_add_u32_e32 v198, v249, v245
	v_add_u32_e32 v200, 0x10000, v194
	v_add_u32_e32 v202, 0x10000, v196
	v_subrev_u32_e32 v249, 0x200, v248
	v_add_u32_e32 v249, v249, v245
	v_add_u32_e32 v250, 0x20100, v245
	v_cndmask_b32_e64 v192, v249, v250, s[38:39]
	v_add_u32_e32 v249, 0x16200, v248
	v_add_u32_e32 v249, v249, v247
	v_add_u32_e32 v250, 0x20300, v247
	v_cndmask_b32_e64 v204, v249, v250, s[40:41]
	v_add_u32_e32 v244, 2, v132
	v_xor_b32_e32 v245, v244, v135
	v_xor_b32_e32 v246, v244, v128
	v_xor_b32_e32 v247, v244, v137
	v_lshl_add_u32 v245, v245, 4, v133
	v_lshl_add_u32 v246, v246, 4, v133
	v_lshl_add_u32 v247, v247, 4, v133
	v_lshlrev_b32_e32 v248, 9, v134
	v_add_u32_e32 v195, v248, v246
	v_add_u32_e32 v249, 0x200, v248
	v_add_u32_e32 v197, v249, v247
	v_add_u32_e32 v249, 0x1e00, v248
	v_add_u32_e32 v191, v249, v245
	v_add_u32_e32 v249, 0xfe00, v248
	v_add_u32_e32 v199, v249, v245
	v_add_u32_e32 v201, 0x10000, v195
	v_add_u32_e32 v203, 0x10000, v197
	v_subrev_u32_e32 v249, 0x200, v248
	v_add_u32_e32 v249, v249, v245
	v_add_u32_e32 v250, 0x20100, v245
	v_cndmask_b32_e64 v193, v249, v250, s[38:39]
	v_add_u32_e32 v249, 0x16200, v248
	v_add_u32_e32 v249, v249, v247
	v_add_u32_e32 v250, 0x20300, v247
	v_cndmask_b32_e64 v205, v249, v250, s[40:41]
	s_waitcnt vmcnt(7) lgkmcnt(0)
	s_barrier
	ds_read_b64 v[232:233], v192
	ds_read_b64 v[234:235], v194
	ds_read_b64 v[236:237], v196
	ds_read_b64 v[238:239], v193
	ds_read_b64 v[240:241], v195
	ds_read_b64 v[242:243], v197
	s_waitcnt lgkmcnt(3)
	v_lshlrev_b32_e32 v244, 16, v232
	v_and_b32_e32 v245, 0xffff0000, v232
	v_lshlrev_b32_e32 v246, 16, v233
	v_and_b32_e32 v247, 0xffff0000, v233
	v_mul_f32_e32 v248, v142, v244
	v_mul_f32_e32 v249, v143, v245
	v_mul_f32_e32 v250, v144, v246
	v_mul_f32_e32 v251, v145, v247
	v_lshlrev_b32_e32 v244, 16, v234
	v_and_b32_e32 v245, 0xffff0000, v234
	v_lshlrev_b32_e32 v246, 16, v235
	v_and_b32_e32 v247, 0xffff0000, v235
	v_fmac_f32_e32 v248, v146, v244
	v_fmac_f32_e32 v249, v147, v245
	v_fmac_f32_e32 v250, v148, v246
	v_fmac_f32_e32 v251, v149, v247
	v_lshlrev_b32_e32 v244, 16, v236
	v_and_b32_e32 v245, 0xffff0000, v236
	v_lshlrev_b32_e32 v246, 16, v237
	v_and_b32_e32 v247, 0xffff0000, v237
	v_fmac_f32_e32 v248, v150, v244
	v_fmac_f32_e32 v249, v151, v245
	v_fmac_f32_e32 v250, v152, v246
	v_fmac_f32_e32 v251, v153, v247
	v_mul_f32_e32 v244, 0xbfb8aa3b, v248
	v_mul_f32_e32 v245, 0xbfb8aa3b, v249
	v_mul_f32_e32 v246, 0xbfb8aa3b, v250
	v_mul_f32_e32 v247, 0xbfb8aa3b, v251
	v_exp_f32_e32 v244, v244
	v_exp_f32_e32 v245, v245
	v_exp_f32_e32 v246, v246
	v_exp_f32_e32 v247, v247
	v_add_f32_e32 v244, 1.0, v244
	v_add_f32_e32 v245, 1.0, v245
	v_add_f32_e32 v246, 1.0, v246
	v_add_f32_e32 v247, 1.0, v247
	v_rcp_f32_e32 v244, v244
	v_rcp_f32_e32 v245, v245
	v_rcp_f32_e32 v246, v246
	v_rcp_f32_e32 v247, v247
	v_mul_f32_e32 v248, v248, v244
	v_mul_f32_e32 v249, v249, v245
	v_mul_f32_e32 v250, v250, v246
	v_mul_f32_e32 v251, v251, v247
	v_mul_f32_e32 v138, v138, v248
	v_mul_f32_e32 v139, v139, v249
	v_mul_f32_e32 v140, v140, v250
	v_mul_f32_e32 v141, v141, v251
	v_cvt_pk_bf16_f32 v138, v138, v139
	v_cvt_pk_bf16_f32 v139, v140, v141
	ds_read_b64 v[232:233], v192 offset:256
	ds_read_b64 v[234:235], v194 offset:256
	ds_read_b64 v[236:237], v196 offset:256
	s_waitcnt lgkmcnt(3)
	v_lshlrev_b32_e32 v244, 16, v238
	v_and_b32_e32 v245, 0xffff0000, v238
	v_lshlrev_b32_e32 v246, 16, v239
	v_and_b32_e32 v247, 0xffff0000, v239
	v_mul_f32_e32 v248, v154, v244
	v_mul_f32_e32 v249, v155, v245
	v_mul_f32_e32 v250, v156, v246
	v_mul_f32_e32 v251, v157, v247
	v_lshlrev_b32_e32 v244, 16, v240
	v_and_b32_e32 v245, 0xffff0000, v240
	v_lshlrev_b32_e32 v246, 16, v241
	v_and_b32_e32 v247, 0xffff0000, v241
	v_fmac_f32_e32 v248, v158, v244
	v_fmac_f32_e32 v249, v159, v245
	v_fmac_f32_e32 v250, v160, v246
	v_fmac_f32_e32 v251, v161, v247
	v_lshlrev_b32_e32 v244, 16, v242
	v_and_b32_e32 v245, 0xffff0000, v242
	v_lshlrev_b32_e32 v246, 16, v243
	v_and_b32_e32 v247, 0xffff0000, v243
	v_fmac_f32_e32 v248, v162, v244
	v_fmac_f32_e32 v249, v163, v245
	v_fmac_f32_e32 v250, v164, v246
	v_fmac_f32_e32 v251, v165, v247
	v_mul_f32_e32 v244, 0xbfb8aa3b, v248
	v_mul_f32_e32 v245, 0xbfb8aa3b, v249
	v_mul_f32_e32 v246, 0xbfb8aa3b, v250
	v_mul_f32_e32 v247, 0xbfb8aa3b, v251
	v_exp_f32_e32 v244, v244
	v_exp_f32_e32 v245, v245
	v_exp_f32_e32 v246, v246
	v_exp_f32_e32 v247, v247
	v_add_f32_e32 v244, 1.0, v244
	v_add_f32_e32 v245, 1.0, v245
	v_add_f32_e32 v246, 1.0, v246
	v_add_f32_e32 v247, 1.0, v247
	v_rcp_f32_e32 v244, v244
	v_rcp_f32_e32 v245, v245
	v_rcp_f32_e32 v246, v246
	v_rcp_f32_e32 v247, v247
	v_mul_f32_e32 v248, v248, v244
	v_mul_f32_e32 v249, v249, v245
	v_mul_f32_e32 v250, v250, v246
	v_mul_f32_e32 v251, v251, v247
	v_mul_f32_e32 v122, v122, v248
	v_mul_f32_e32 v123, v123, v249
	v_mul_f32_e32 v124, v124, v250
	v_mul_f32_e32 v125, v125, v251
	v_cvt_pk_bf16_f32 v122, v122, v123
	v_cvt_pk_bf16_f32 v123, v124, v125
	ds_read_b64 v[238:239], v193 offset:256
	ds_read_b64 v[240:241], v195 offset:256
	ds_read_b64 v[242:243], v197 offset:256
	s_waitcnt lgkmcnt(3)
	v_lshlrev_b32_e32 v244, 16, v232
	v_and_b32_e32 v245, 0xffff0000, v232
	v_lshlrev_b32_e32 v246, 16, v233
	v_and_b32_e32 v247, 0xffff0000, v233
	v_mul_f32_e32 v248, v166, v244
	v_mul_f32_e32 v249, v167, v245
	v_mul_f32_e32 v250, v168, v246
	v_mul_f32_e32 v251, v169, v247
	v_lshlrev_b32_e32 v244, 16, v234
	v_and_b32_e32 v245, 0xffff0000, v234
	v_lshlrev_b32_e32 v246, 16, v235
	v_and_b32_e32 v247, 0xffff0000, v235
	v_fmac_f32_e32 v248, v170, v244
	v_fmac_f32_e32 v249, v171, v245
	v_fmac_f32_e32 v250, v172, v246
	v_fmac_f32_e32 v251, v173, v247
	v_lshlrev_b32_e32 v244, 16, v236
	v_and_b32_e32 v245, 0xffff0000, v236
	v_lshlrev_b32_e32 v246, 16, v237
	v_and_b32_e32 v247, 0xffff0000, v237
	v_fmac_f32_e32 v248, v174, v244
	v_fmac_f32_e32 v249, v175, v245
	v_fmac_f32_e32 v250, v176, v246
	v_fmac_f32_e32 v251, v177, v247
	v_mul_f32_e32 v244, 0xbfb8aa3b, v248
	v_mul_f32_e32 v245, 0xbfb8aa3b, v249
	v_mul_f32_e32 v246, 0xbfb8aa3b, v250
	v_mul_f32_e32 v247, 0xbfb8aa3b, v251
	v_exp_f32_e32 v244, v244
	v_exp_f32_e32 v245, v245
	v_exp_f32_e32 v246, v246
	v_exp_f32_e32 v247, v247
	v_add_f32_e32 v244, 1.0, v244
	v_add_f32_e32 v245, 1.0, v245
	v_add_f32_e32 v246, 1.0, v246
	v_add_f32_e32 v247, 1.0, v247
	v_rcp_f32_e32 v244, v244
	v_rcp_f32_e32 v245, v245
	v_rcp_f32_e32 v246, v246
	v_rcp_f32_e32 v247, v247
	v_mul_f32_e32 v248, v248, v244
	v_mul_f32_e32 v249, v249, v245
	v_mul_f32_e32 v250, v250, v246
	v_mul_f32_e32 v251, v251, v247
	v_mul_f32_e32 v118, v118, v248
	v_mul_f32_e32 v119, v119, v249
	v_mul_f32_e32 v120, v120, v250
	v_mul_f32_e32 v121, v121, v251
	v_cvt_pk_bf16_f32 v118, v118, v119
	v_cvt_pk_bf16_f32 v119, v120, v121
	ds_read_b64 v[232:233], v190
	ds_read_b64 v[234:235], v194 offset:8192
	ds_read_b64 v[236:237], v196 offset:8192
	s_waitcnt lgkmcnt(3)
	v_lshlrev_b32_e32 v244, 16, v238
	v_and_b32_e32 v245, 0xffff0000, v238
	v_lshlrev_b32_e32 v246, 16, v239
	v_and_b32_e32 v247, 0xffff0000, v239
	v_mul_f32_e32 v248, v178, v244
	v_mul_f32_e32 v249, v179, v245
	v_mul_f32_e32 v250, v180, v246
	v_mul_f32_e32 v251, v181, v247
	v_lshlrev_b32_e32 v244, 16, v240
	v_and_b32_e32 v245, 0xffff0000, v240
	v_lshlrev_b32_e32 v246, 16, v241
	v_and_b32_e32 v247, 0xffff0000, v241
	v_fmac_f32_e32 v248, v182, v244
	v_fmac_f32_e32 v249, v183, v245
	v_fmac_f32_e32 v250, v184, v246
	v_fmac_f32_e32 v251, v185, v247
	v_lshlrev_b32_e32 v244, 16, v242
	v_and_b32_e32 v245, 0xffff0000, v242
	v_lshlrev_b32_e32 v246, 16, v243
	v_and_b32_e32 v247, 0xffff0000, v243
	v_fmac_f32_e32 v248, v186, v244
	v_fmac_f32_e32 v249, v187, v245
	v_fmac_f32_e32 v250, v188, v246
	v_fmac_f32_e32 v251, v189, v247
	v_mul_f32_e32 v244, 0xbfb8aa3b, v248
	v_mul_f32_e32 v245, 0xbfb8aa3b, v249
	v_mul_f32_e32 v246, 0xbfb8aa3b, v250
	v_mul_f32_e32 v247, 0xbfb8aa3b, v251
	v_exp_f32_e32 v244, v244
	v_exp_f32_e32 v245, v245
	v_exp_f32_e32 v246, v246
	v_exp_f32_e32 v247, v247
	v_add_f32_e32 v244, 1.0, v244
	v_add_f32_e32 v245, 1.0, v245
	v_add_f32_e32 v246, 1.0, v246
	v_add_f32_e32 v247, 1.0, v247
	v_rcp_f32_e32 v244, v244
	v_rcp_f32_e32 v245, v245
	v_rcp_f32_e32 v246, v246
	v_rcp_f32_e32 v247, v247
	v_mul_f32_e32 v248, v248, v244
	v_mul_f32_e32 v249, v249, v245
	v_mul_f32_e32 v250, v250, v246
	v_mul_f32_e32 v251, v251, v247
	v_mul_f32_e32 v114, v114, v248
	v_mul_f32_e32 v115, v115, v249
	v_mul_f32_e32 v116, v116, v250
	v_mul_f32_e32 v117, v117, v251
	v_cvt_pk_bf16_f32 v114, v114, v115
	v_cvt_pk_bf16_f32 v115, v116, v117
	ds_read_b64 v[238:239], v191
	ds_read_b64 v[240:241], v195 offset:8192
	ds_read_b64 v[242:243], v197 offset:8192
	s_waitcnt lgkmcnt(3)
	v_lshlrev_b32_e32 v244, 16, v232
	v_and_b32_e32 v245, 0xffff0000, v232
	v_lshlrev_b32_e32 v246, 16, v233
	v_and_b32_e32 v247, 0xffff0000, v233
	v_mul_f32_e32 v248, v142, v244
	v_mul_f32_e32 v249, v143, v245
	v_mul_f32_e32 v250, v144, v246
	v_mul_f32_e32 v251, v145, v247
	v_lshlrev_b32_e32 v244, 16, v234
	v_and_b32_e32 v245, 0xffff0000, v234
	v_lshlrev_b32_e32 v246, 16, v235
	v_and_b32_e32 v247, 0xffff0000, v235
	v_fmac_f32_e32 v248, v146, v244
	v_fmac_f32_e32 v249, v147, v245
	v_fmac_f32_e32 v250, v148, v246
	v_fmac_f32_e32 v251, v149, v247
	v_lshlrev_b32_e32 v244, 16, v236
	v_and_b32_e32 v245, 0xffff0000, v236
	v_lshlrev_b32_e32 v246, 16, v237
	v_and_b32_e32 v247, 0xffff0000, v237
	v_fmac_f32_e32 v248, v150, v244
	v_fmac_f32_e32 v249, v151, v245
	v_fmac_f32_e32 v250, v152, v246
	v_fmac_f32_e32 v251, v153, v247
	v_mul_f32_e32 v244, 0xbfb8aa3b, v248
	v_mul_f32_e32 v245, 0xbfb8aa3b, v249
	v_mul_f32_e32 v246, 0xbfb8aa3b, v250
	v_mul_f32_e32 v247, 0xbfb8aa3b, v251
	v_exp_f32_e32 v244, v244
	v_exp_f32_e32 v245, v245
	v_exp_f32_e32 v246, v246
	v_exp_f32_e32 v247, v247
	v_add_f32_e32 v244, 1.0, v244
	v_add_f32_e32 v245, 1.0, v245
	v_add_f32_e32 v246, 1.0, v246
	v_add_f32_e32 v247, 1.0, v247
	v_rcp_f32_e32 v244, v244
	v_rcp_f32_e32 v245, v245
	v_rcp_f32_e32 v246, v246
	v_rcp_f32_e32 v247, v247
	v_mul_f32_e32 v248, v248, v244
	v_mul_f32_e32 v249, v249, v245
	v_mul_f32_e32 v250, v250, v246
	v_mul_f32_e32 v251, v251, v247
	v_mul_f32_e32 v110, v110, v248
	v_mul_f32_e32 v111, v111, v249
	v_mul_f32_e32 v112, v112, v250
	v_mul_f32_e32 v113, v113, v251
	v_cvt_pk_bf16_f32 v110, v110, v111
	v_cvt_pk_bf16_f32 v111, v112, v113
	ds_read_b64 v[232:233], v190 offset:256
	ds_read_b64 v[234:235], v194 offset:8448
	ds_read_b64 v[236:237], v196 offset:8448
	s_waitcnt lgkmcnt(3)
	v_lshlrev_b32_e32 v244, 16, v238
	v_and_b32_e32 v245, 0xffff0000, v238
	v_lshlrev_b32_e32 v246, 16, v239
	v_and_b32_e32 v247, 0xffff0000, v239
	v_mul_f32_e32 v248, v154, v244
	v_mul_f32_e32 v249, v155, v245
	v_mul_f32_e32 v250, v156, v246
	v_mul_f32_e32 v251, v157, v247
	v_lshlrev_b32_e32 v244, 16, v240
	v_and_b32_e32 v245, 0xffff0000, v240
	v_lshlrev_b32_e32 v246, 16, v241
	v_and_b32_e32 v247, 0xffff0000, v241
	v_fmac_f32_e32 v248, v158, v244
	v_fmac_f32_e32 v249, v159, v245
	v_fmac_f32_e32 v250, v160, v246
	v_fmac_f32_e32 v251, v161, v247
	v_lshlrev_b32_e32 v244, 16, v242
	v_and_b32_e32 v245, 0xffff0000, v242
	v_lshlrev_b32_e32 v246, 16, v243
	v_and_b32_e32 v247, 0xffff0000, v243
	v_fmac_f32_e32 v248, v162, v244
	v_fmac_f32_e32 v249, v163, v245
	v_fmac_f32_e32 v250, v164, v246
	v_fmac_f32_e32 v251, v165, v247
	v_mul_f32_e32 v244, 0xbfb8aa3b, v248
	v_mul_f32_e32 v245, 0xbfb8aa3b, v249
	v_mul_f32_e32 v246, 0xbfb8aa3b, v250
	v_mul_f32_e32 v247, 0xbfb8aa3b, v251
	v_exp_f32_e32 v244, v244
	v_exp_f32_e32 v245, v245
	v_exp_f32_e32 v246, v246
	v_exp_f32_e32 v247, v247
	v_add_f32_e32 v244, 1.0, v244
	v_add_f32_e32 v245, 1.0, v245
	v_add_f32_e32 v246, 1.0, v246
	v_add_f32_e32 v247, 1.0, v247
	v_rcp_f32_e32 v244, v244
	v_rcp_f32_e32 v245, v245
	v_rcp_f32_e32 v246, v246
	v_rcp_f32_e32 v247, v247
	v_mul_f32_e32 v248, v248, v244
	v_mul_f32_e32 v249, v249, v245
	v_mul_f32_e32 v250, v250, v246
	v_mul_f32_e32 v251, v251, v247
	v_mul_f32_e32 v106, v106, v248
	v_mul_f32_e32 v107, v107, v249
	v_mul_f32_e32 v108, v108, v250
	v_mul_f32_e32 v109, v109, v251
	v_cvt_pk_bf16_f32 v106, v106, v107
	v_cvt_pk_bf16_f32 v107, v108, v109
	ds_read_b64 v[238:239], v191 offset:256
	ds_read_b64 v[240:241], v195 offset:8448
	ds_read_b64 v[242:243], v197 offset:8448
	s_waitcnt lgkmcnt(3)
	v_lshlrev_b32_e32 v244, 16, v232
	v_and_b32_e32 v245, 0xffff0000, v232
	v_lshlrev_b32_e32 v246, 16, v233
	v_and_b32_e32 v247, 0xffff0000, v233
	v_mul_f32_e32 v248, v166, v244
	v_mul_f32_e32 v249, v167, v245
	v_mul_f32_e32 v250, v168, v246
	v_mul_f32_e32 v251, v169, v247
	v_lshlrev_b32_e32 v244, 16, v234
	v_and_b32_e32 v245, 0xffff0000, v234
	v_lshlrev_b32_e32 v246, 16, v235
	v_and_b32_e32 v247, 0xffff0000, v235
	v_fmac_f32_e32 v248, v170, v244
	v_fmac_f32_e32 v249, v171, v245
	v_fmac_f32_e32 v250, v172, v246
	v_fmac_f32_e32 v251, v173, v247
	v_lshlrev_b32_e32 v244, 16, v236
	v_and_b32_e32 v245, 0xffff0000, v236
	v_lshlrev_b32_e32 v246, 16, v237
	v_and_b32_e32 v247, 0xffff0000, v237
	v_fmac_f32_e32 v248, v174, v244
	v_fmac_f32_e32 v249, v175, v245
	v_fmac_f32_e32 v250, v176, v246
	v_fmac_f32_e32 v251, v177, v247
	v_mul_f32_e32 v244, 0xbfb8aa3b, v248
	v_mul_f32_e32 v245, 0xbfb8aa3b, v249
	v_mul_f32_e32 v246, 0xbfb8aa3b, v250
	v_mul_f32_e32 v247, 0xbfb8aa3b, v251
	v_exp_f32_e32 v244, v244
	v_exp_f32_e32 v245, v245
	v_exp_f32_e32 v246, v246
	v_exp_f32_e32 v247, v247
	v_add_f32_e32 v244, 1.0, v244
	v_add_f32_e32 v245, 1.0, v245
	v_add_f32_e32 v246, 1.0, v246
	v_add_f32_e32 v247, 1.0, v247
	v_rcp_f32_e32 v244, v244
	v_rcp_f32_e32 v245, v245
	v_rcp_f32_e32 v246, v246
	v_rcp_f32_e32 v247, v247
	v_mul_f32_e32 v248, v248, v244
	v_mul_f32_e32 v249, v249, v245
	v_mul_f32_e32 v250, v250, v246
	v_mul_f32_e32 v251, v251, v247
	v_mul_f32_e32 v102, v102, v248
	v_mul_f32_e32 v103, v103, v249
	v_mul_f32_e32 v104, v104, v250
	v_mul_f32_e32 v105, v105, v251
	v_cvt_pk_bf16_f32 v102, v102, v103
	v_cvt_pk_bf16_f32 v103, v104, v105
	ds_read_b64 v[232:233], v190 offset:8192
	ds_read_b64 v[234:235], v194 offset:16384
	ds_read_b64 v[236:237], v196 offset:16384
	s_waitcnt lgkmcnt(3)
	v_lshlrev_b32_e32 v244, 16, v238
	v_and_b32_e32 v245, 0xffff0000, v238
	v_lshlrev_b32_e32 v246, 16, v239
	v_and_b32_e32 v247, 0xffff0000, v239
	v_mul_f32_e32 v248, v178, v244
	v_mul_f32_e32 v249, v179, v245
	v_mul_f32_e32 v250, v180, v246
	v_mul_f32_e32 v251, v181, v247
	v_lshlrev_b32_e32 v244, 16, v240
	v_and_b32_e32 v245, 0xffff0000, v240
	v_lshlrev_b32_e32 v246, 16, v241
	v_and_b32_e32 v247, 0xffff0000, v241
	v_fmac_f32_e32 v248, v182, v244
	v_fmac_f32_e32 v249, v183, v245
	v_fmac_f32_e32 v250, v184, v246
	v_fmac_f32_e32 v251, v185, v247
	v_lshlrev_b32_e32 v244, 16, v242
	v_and_b32_e32 v245, 0xffff0000, v242
	v_lshlrev_b32_e32 v246, 16, v243
	v_and_b32_e32 v247, 0xffff0000, v243
	v_fmac_f32_e32 v248, v186, v244
	v_fmac_f32_e32 v249, v187, v245
	v_fmac_f32_e32 v250, v188, v246
	v_fmac_f32_e32 v251, v189, v247
	v_mul_f32_e32 v244, 0xbfb8aa3b, v248
	v_mul_f32_e32 v245, 0xbfb8aa3b, v249
	v_mul_f32_e32 v246, 0xbfb8aa3b, v250
	v_mul_f32_e32 v247, 0xbfb8aa3b, v251
	v_exp_f32_e32 v244, v244
	v_exp_f32_e32 v245, v245
	v_exp_f32_e32 v246, v246
	v_exp_f32_e32 v247, v247
	v_add_f32_e32 v244, 1.0, v244
	v_add_f32_e32 v245, 1.0, v245
	v_add_f32_e32 v246, 1.0, v246
	v_add_f32_e32 v247, 1.0, v247
	v_rcp_f32_e32 v244, v244
	v_rcp_f32_e32 v245, v245
	v_rcp_f32_e32 v246, v246
	v_rcp_f32_e32 v247, v247
	v_mul_f32_e32 v248, v248, v244
	v_mul_f32_e32 v249, v249, v245
	v_mul_f32_e32 v250, v250, v246
	v_mul_f32_e32 v251, v251, v247
	v_mul_f32_e32 v98, v98, v248
	v_mul_f32_e32 v99, v99, v249
	v_mul_f32_e32 v100, v100, v250
	v_mul_f32_e32 v101, v101, v251
	v_cvt_pk_bf16_f32 v98, v98, v99
	v_cvt_pk_bf16_f32 v99, v100, v101
	ds_read_b64 v[238:239], v191 offset:8192
	ds_read_b64 v[240:241], v195 offset:16384
	ds_read_b64 v[242:243], v197 offset:16384
	s_waitcnt lgkmcnt(3)
	v_lshlrev_b32_e32 v244, 16, v232
	v_and_b32_e32 v245, 0xffff0000, v232
	v_lshlrev_b32_e32 v246, 16, v233
	v_and_b32_e32 v247, 0xffff0000, v233
	v_mul_f32_e32 v248, v142, v244
	v_mul_f32_e32 v249, v143, v245
	v_mul_f32_e32 v250, v144, v246
	v_mul_f32_e32 v251, v145, v247
	v_lshlrev_b32_e32 v244, 16, v234
	v_and_b32_e32 v245, 0xffff0000, v234
	v_lshlrev_b32_e32 v246, 16, v235
	v_and_b32_e32 v247, 0xffff0000, v235
	v_fmac_f32_e32 v248, v146, v244
	v_fmac_f32_e32 v249, v147, v245
	v_fmac_f32_e32 v250, v148, v246
	v_fmac_f32_e32 v251, v149, v247
	v_lshlrev_b32_e32 v244, 16, v236
	v_and_b32_e32 v245, 0xffff0000, v236
	v_lshlrev_b32_e32 v246, 16, v237
	v_and_b32_e32 v247, 0xffff0000, v237
	v_fmac_f32_e32 v248, v150, v244
	v_fmac_f32_e32 v249, v151, v245
	v_fmac_f32_e32 v250, v152, v246
	v_fmac_f32_e32 v251, v153, v247
	v_mul_f32_e32 v244, 0xbfb8aa3b, v248
	v_mul_f32_e32 v245, 0xbfb8aa3b, v249
	v_mul_f32_e32 v246, 0xbfb8aa3b, v250
	v_mul_f32_e32 v247, 0xbfb8aa3b, v251
	v_exp_f32_e32 v244, v244
	v_exp_f32_e32 v245, v245
	v_exp_f32_e32 v246, v246
	v_exp_f32_e32 v247, v247
	v_add_f32_e32 v244, 1.0, v244
	v_add_f32_e32 v245, 1.0, v245
	v_add_f32_e32 v246, 1.0, v246
	v_add_f32_e32 v247, 1.0, v247
	v_rcp_f32_e32 v244, v244
	v_rcp_f32_e32 v245, v245
	v_rcp_f32_e32 v246, v246
	v_rcp_f32_e32 v247, v247
	v_mul_f32_e32 v248, v248, v244
	v_mul_f32_e32 v249, v249, v245
	v_mul_f32_e32 v250, v250, v246
	v_mul_f32_e32 v251, v251, v247
	v_mul_f32_e32 v94, v94, v248
	v_mul_f32_e32 v95, v95, v249
	v_mul_f32_e32 v96, v96, v250
	v_mul_f32_e32 v97, v97, v251
	v_cvt_pk_bf16_f32 v94, v94, v95
	v_cvt_pk_bf16_f32 v95, v96, v97
	ds_read_b64 v[232:233], v190 offset:8448
	ds_read_b64 v[234:235], v194 offset:16640
	ds_read_b64 v[236:237], v196 offset:16640
	s_waitcnt lgkmcnt(3)
	v_lshlrev_b32_e32 v244, 16, v238
	v_and_b32_e32 v245, 0xffff0000, v238
	v_lshlrev_b32_e32 v246, 16, v239
	v_and_b32_e32 v247, 0xffff0000, v239
	v_mul_f32_e32 v248, v154, v244
	v_mul_f32_e32 v249, v155, v245
	v_mul_f32_e32 v250, v156, v246
	v_mul_f32_e32 v251, v157, v247
	v_lshlrev_b32_e32 v244, 16, v240
	v_and_b32_e32 v245, 0xffff0000, v240
	v_lshlrev_b32_e32 v246, 16, v241
	v_and_b32_e32 v247, 0xffff0000, v241
	v_fmac_f32_e32 v248, v158, v244
	v_fmac_f32_e32 v249, v159, v245
	v_fmac_f32_e32 v250, v160, v246
	v_fmac_f32_e32 v251, v161, v247
	v_lshlrev_b32_e32 v244, 16, v242
	v_and_b32_e32 v245, 0xffff0000, v242
	v_lshlrev_b32_e32 v246, 16, v243
	v_and_b32_e32 v247, 0xffff0000, v243
	v_fmac_f32_e32 v248, v162, v244
	v_fmac_f32_e32 v249, v163, v245
	v_fmac_f32_e32 v250, v164, v246
	v_fmac_f32_e32 v251, v165, v247
	v_mul_f32_e32 v244, 0xbfb8aa3b, v248
	v_mul_f32_e32 v245, 0xbfb8aa3b, v249
	v_mul_f32_e32 v246, 0xbfb8aa3b, v250
	v_mul_f32_e32 v247, 0xbfb8aa3b, v251
	v_exp_f32_e32 v244, v244
	v_exp_f32_e32 v245, v245
	v_exp_f32_e32 v246, v246
	v_exp_f32_e32 v247, v247
	v_add_f32_e32 v244, 1.0, v244
	v_add_f32_e32 v245, 1.0, v245
	v_add_f32_e32 v246, 1.0, v246
	v_add_f32_e32 v247, 1.0, v247
	v_rcp_f32_e32 v244, v244
	v_rcp_f32_e32 v245, v245
	v_rcp_f32_e32 v246, v246
	v_rcp_f32_e32 v247, v247
	v_mul_f32_e32 v248, v248, v244
	v_mul_f32_e32 v249, v249, v245
	v_mul_f32_e32 v250, v250, v246
	v_mul_f32_e32 v251, v251, v247
	v_mul_f32_e32 v90, v90, v248
	v_mul_f32_e32 v91, v91, v249
	v_mul_f32_e32 v92, v92, v250
	v_mul_f32_e32 v93, v93, v251
	v_cvt_pk_bf16_f32 v90, v90, v91
	v_cvt_pk_bf16_f32 v91, v92, v93
	ds_read_b64 v[238:239], v191 offset:8448
	ds_read_b64 v[240:241], v195 offset:16640
	ds_read_b64 v[242:243], v197 offset:16640
	s_waitcnt lgkmcnt(3)
	v_lshlrev_b32_e32 v244, 16, v232
	v_and_b32_e32 v245, 0xffff0000, v232
	v_lshlrev_b32_e32 v246, 16, v233
	v_and_b32_e32 v247, 0xffff0000, v233
	v_mul_f32_e32 v248, v166, v244
	v_mul_f32_e32 v249, v167, v245
	v_mul_f32_e32 v250, v168, v246
	v_mul_f32_e32 v251, v169, v247
	v_lshlrev_b32_e32 v244, 16, v234
	v_and_b32_e32 v245, 0xffff0000, v234
	v_lshlrev_b32_e32 v246, 16, v235
	v_and_b32_e32 v247, 0xffff0000, v235
	v_fmac_f32_e32 v248, v170, v244
	v_fmac_f32_e32 v249, v171, v245
	v_fmac_f32_e32 v250, v172, v246
	v_fmac_f32_e32 v251, v173, v247
	v_lshlrev_b32_e32 v244, 16, v236
	v_and_b32_e32 v245, 0xffff0000, v236
	v_lshlrev_b32_e32 v246, 16, v237
	v_and_b32_e32 v247, 0xffff0000, v237
	v_fmac_f32_e32 v248, v174, v244
	v_fmac_f32_e32 v249, v175, v245
	v_fmac_f32_e32 v250, v176, v246
	v_fmac_f32_e32 v251, v177, v247
	v_mul_f32_e32 v244, 0xbfb8aa3b, v248
	v_mul_f32_e32 v245, 0xbfb8aa3b, v249
	v_mul_f32_e32 v246, 0xbfb8aa3b, v250
	v_mul_f32_e32 v247, 0xbfb8aa3b, v251
	v_exp_f32_e32 v244, v244
	v_exp_f32_e32 v245, v245
	v_exp_f32_e32 v246, v246
	v_exp_f32_e32 v247, v247
	v_add_f32_e32 v244, 1.0, v244
	v_add_f32_e32 v245, 1.0, v245
	v_add_f32_e32 v246, 1.0, v246
	v_add_f32_e32 v247, 1.0, v247
	v_rcp_f32_e32 v244, v244
	v_rcp_f32_e32 v245, v245
	v_rcp_f32_e32 v246, v246
	v_rcp_f32_e32 v247, v247
	v_mul_f32_e32 v248, v248, v244
	v_mul_f32_e32 v249, v249, v245
	v_mul_f32_e32 v250, v250, v246
	v_mul_f32_e32 v251, v251, v247
	v_mul_f32_e32 v86, v86, v248
	v_mul_f32_e32 v87, v87, v249
	v_mul_f32_e32 v88, v88, v250
	v_mul_f32_e32 v89, v89, v251
	v_cvt_pk_bf16_f32 v86, v86, v87
	v_cvt_pk_bf16_f32 v87, v88, v89
	ds_read_b64 v[232:233], v190 offset:16384
	ds_read_b64 v[234:235], v194 offset:24576
	ds_read_b64 v[236:237], v196 offset:24576
	s_waitcnt lgkmcnt(3)
	v_lshlrev_b32_e32 v244, 16, v238
	v_and_b32_e32 v245, 0xffff0000, v238
	v_lshlrev_b32_e32 v246, 16, v239
	v_and_b32_e32 v247, 0xffff0000, v239
	v_mul_f32_e32 v248, v178, v244
	v_mul_f32_e32 v249, v179, v245
	v_mul_f32_e32 v250, v180, v246
	v_mul_f32_e32 v251, v181, v247
	v_lshlrev_b32_e32 v244, 16, v240
	v_and_b32_e32 v245, 0xffff0000, v240
	v_lshlrev_b32_e32 v246, 16, v241
	v_and_b32_e32 v247, 0xffff0000, v241
	v_fmac_f32_e32 v248, v182, v244
	v_fmac_f32_e32 v249, v183, v245
	v_fmac_f32_e32 v250, v184, v246
	v_fmac_f32_e32 v251, v185, v247
	v_lshlrev_b32_e32 v244, 16, v242
	v_and_b32_e32 v245, 0xffff0000, v242
	v_lshlrev_b32_e32 v246, 16, v243
	v_and_b32_e32 v247, 0xffff0000, v243
	v_fmac_f32_e32 v248, v186, v244
	v_fmac_f32_e32 v249, v187, v245
	v_fmac_f32_e32 v250, v188, v246
	v_fmac_f32_e32 v251, v189, v247
	v_mul_f32_e32 v244, 0xbfb8aa3b, v248
	v_mul_f32_e32 v245, 0xbfb8aa3b, v249
	v_mul_f32_e32 v246, 0xbfb8aa3b, v250
	v_mul_f32_e32 v247, 0xbfb8aa3b, v251
	v_exp_f32_e32 v244, v244
	v_exp_f32_e32 v245, v245
	v_exp_f32_e32 v246, v246
	v_exp_f32_e32 v247, v247
	v_add_f32_e32 v244, 1.0, v244
	v_add_f32_e32 v245, 1.0, v245
	v_add_f32_e32 v246, 1.0, v246
	v_add_f32_e32 v247, 1.0, v247
	v_rcp_f32_e32 v244, v244
	v_rcp_f32_e32 v245, v245
	v_rcp_f32_e32 v246, v246
	v_rcp_f32_e32 v247, v247
	v_mul_f32_e32 v248, v248, v244
	v_mul_f32_e32 v249, v249, v245
	v_mul_f32_e32 v250, v250, v246
	v_mul_f32_e32 v251, v251, v247
	v_mul_f32_e32 v82, v82, v248
	v_mul_f32_e32 v83, v83, v249
	v_mul_f32_e32 v84, v84, v250
	v_mul_f32_e32 v85, v85, v251
	v_cvt_pk_bf16_f32 v82, v82, v83
	v_cvt_pk_bf16_f32 v83, v84, v85
	ds_read_b64 v[238:239], v191 offset:16384
	ds_read_b64 v[240:241], v195 offset:24576
	ds_read_b64 v[242:243], v197 offset:24576
	s_waitcnt lgkmcnt(3)
	v_lshlrev_b32_e32 v244, 16, v232
	v_and_b32_e32 v245, 0xffff0000, v232
	v_lshlrev_b32_e32 v246, 16, v233
	v_and_b32_e32 v247, 0xffff0000, v233
	v_mul_f32_e32 v248, v142, v244
	v_mul_f32_e32 v249, v143, v245
	v_mul_f32_e32 v250, v144, v246
	v_mul_f32_e32 v251, v145, v247
	v_lshlrev_b32_e32 v244, 16, v234
	v_and_b32_e32 v245, 0xffff0000, v234
	v_lshlrev_b32_e32 v246, 16, v235
	v_and_b32_e32 v247, 0xffff0000, v235
	v_fmac_f32_e32 v248, v146, v244
	v_fmac_f32_e32 v249, v147, v245
	v_fmac_f32_e32 v250, v148, v246
	v_fmac_f32_e32 v251, v149, v247
	v_lshlrev_b32_e32 v244, 16, v236
	v_and_b32_e32 v245, 0xffff0000, v236
	v_lshlrev_b32_e32 v246, 16, v237
	v_and_b32_e32 v247, 0xffff0000, v237
	v_fmac_f32_e32 v248, v150, v244
	v_fmac_f32_e32 v249, v151, v245
	v_fmac_f32_e32 v250, v152, v246
	v_fmac_f32_e32 v251, v153, v247
	v_mul_f32_e32 v244, 0xbfb8aa3b, v248
	v_mul_f32_e32 v245, 0xbfb8aa3b, v249
	v_mul_f32_e32 v246, 0xbfb8aa3b, v250
	v_mul_f32_e32 v247, 0xbfb8aa3b, v251
	v_exp_f32_e32 v244, v244
	v_exp_f32_e32 v245, v245
	v_exp_f32_e32 v246, v246
	v_exp_f32_e32 v247, v247
	v_add_f32_e32 v244, 1.0, v244
	v_add_f32_e32 v245, 1.0, v245
	v_add_f32_e32 v246, 1.0, v246
	v_add_f32_e32 v247, 1.0, v247
	v_rcp_f32_e32 v244, v244
	v_rcp_f32_e32 v245, v245
	v_rcp_f32_e32 v246, v246
	v_rcp_f32_e32 v247, v247
	v_mul_f32_e32 v248, v248, v244
	v_mul_f32_e32 v249, v249, v245
	v_mul_f32_e32 v250, v250, v246
	v_mul_f32_e32 v251, v251, v247
	v_mul_f32_e32 v78, v78, v248
	v_mul_f32_e32 v79, v79, v249
	v_mul_f32_e32 v80, v80, v250
	v_mul_f32_e32 v81, v81, v251
	v_cvt_pk_bf16_f32 v78, v78, v79
	v_cvt_pk_bf16_f32 v79, v80, v81
	ds_read_b64 v[232:233], v190 offset:16640
	ds_read_b64 v[234:235], v194 offset:24832
	ds_read_b64 v[236:237], v196 offset:24832
	s_waitcnt lgkmcnt(3)
	v_lshlrev_b32_e32 v244, 16, v238
	v_and_b32_e32 v245, 0xffff0000, v238
	v_lshlrev_b32_e32 v246, 16, v239
	v_and_b32_e32 v247, 0xffff0000, v239
	v_mul_f32_e32 v248, v154, v244
	v_mul_f32_e32 v249, v155, v245
	v_mul_f32_e32 v250, v156, v246
	v_mul_f32_e32 v251, v157, v247
	v_lshlrev_b32_e32 v244, 16, v240
	v_and_b32_e32 v245, 0xffff0000, v240
	v_lshlrev_b32_e32 v246, 16, v241
	v_and_b32_e32 v247, 0xffff0000, v241
	v_fmac_f32_e32 v248, v158, v244
	v_fmac_f32_e32 v249, v159, v245
	v_fmac_f32_e32 v250, v160, v246
	v_fmac_f32_e32 v251, v161, v247
	v_lshlrev_b32_e32 v244, 16, v242
	v_and_b32_e32 v245, 0xffff0000, v242
	v_lshlrev_b32_e32 v246, 16, v243
	v_and_b32_e32 v247, 0xffff0000, v243
	v_fmac_f32_e32 v248, v162, v244
	v_fmac_f32_e32 v249, v163, v245
	v_fmac_f32_e32 v250, v164, v246
	v_fmac_f32_e32 v251, v165, v247
	v_mul_f32_e32 v244, 0xbfb8aa3b, v248
	v_mul_f32_e32 v245, 0xbfb8aa3b, v249
	v_mul_f32_e32 v246, 0xbfb8aa3b, v250
	v_mul_f32_e32 v247, 0xbfb8aa3b, v251
	v_exp_f32_e32 v244, v244
	v_exp_f32_e32 v245, v245
	v_exp_f32_e32 v246, v246
	v_exp_f32_e32 v247, v247
	v_add_f32_e32 v244, 1.0, v244
	v_add_f32_e32 v245, 1.0, v245
	v_add_f32_e32 v246, 1.0, v246
	v_add_f32_e32 v247, 1.0, v247
	v_rcp_f32_e32 v244, v244
	v_rcp_f32_e32 v245, v245
	v_rcp_f32_e32 v246, v246
	v_rcp_f32_e32 v247, v247
	v_mul_f32_e32 v248, v248, v244
	v_mul_f32_e32 v249, v249, v245
	v_mul_f32_e32 v250, v250, v246
	v_mul_f32_e32 v251, v251, v247
	v_mul_f32_e32 v74, v74, v248
	v_mul_f32_e32 v75, v75, v249
	v_mul_f32_e32 v76, v76, v250
	v_mul_f32_e32 v77, v77, v251
	v_cvt_pk_bf16_f32 v74, v74, v75
	v_cvt_pk_bf16_f32 v75, v76, v77
	ds_read_b64 v[238:239], v191 offset:16640
	ds_read_b64 v[240:241], v195 offset:24832
	ds_read_b64 v[242:243], v197 offset:24832
	s_waitcnt lgkmcnt(3)
	v_lshlrev_b32_e32 v244, 16, v232
	v_and_b32_e32 v245, 0xffff0000, v232
	v_lshlrev_b32_e32 v246, 16, v233
	v_and_b32_e32 v247, 0xffff0000, v233
	v_mul_f32_e32 v248, v166, v244
	v_mul_f32_e32 v249, v167, v245
	v_mul_f32_e32 v250, v168, v246
	v_mul_f32_e32 v251, v169, v247
	v_lshlrev_b32_e32 v244, 16, v234
	v_and_b32_e32 v245, 0xffff0000, v234
	v_lshlrev_b32_e32 v246, 16, v235
	v_and_b32_e32 v247, 0xffff0000, v235
	v_fmac_f32_e32 v248, v170, v244
	v_fmac_f32_e32 v249, v171, v245
	v_fmac_f32_e32 v250, v172, v246
	v_fmac_f32_e32 v251, v173, v247
	v_lshlrev_b32_e32 v244, 16, v236
	v_and_b32_e32 v245, 0xffff0000, v236
	v_lshlrev_b32_e32 v246, 16, v237
	v_and_b32_e32 v247, 0xffff0000, v237
	v_fmac_f32_e32 v248, v174, v244
	v_fmac_f32_e32 v249, v175, v245
	v_fmac_f32_e32 v250, v176, v246
	v_fmac_f32_e32 v251, v177, v247
	v_mul_f32_e32 v244, 0xbfb8aa3b, v248
	v_mul_f32_e32 v245, 0xbfb8aa3b, v249
	v_mul_f32_e32 v246, 0xbfb8aa3b, v250
	v_mul_f32_e32 v247, 0xbfb8aa3b, v251
	v_exp_f32_e32 v244, v244
	v_exp_f32_e32 v245, v245
	v_exp_f32_e32 v246, v246
	v_exp_f32_e32 v247, v247
	v_add_f32_e32 v244, 1.0, v244
	v_add_f32_e32 v245, 1.0, v245
	v_add_f32_e32 v246, 1.0, v246
	v_add_f32_e32 v247, 1.0, v247
	v_rcp_f32_e32 v244, v244
	v_rcp_f32_e32 v245, v245
	v_rcp_f32_e32 v246, v246
	v_rcp_f32_e32 v247, v247
	v_mul_f32_e32 v248, v248, v244
	v_mul_f32_e32 v249, v249, v245
	v_mul_f32_e32 v250, v250, v246
	v_mul_f32_e32 v251, v251, v247
	v_mul_f32_e32 v70, v70, v248
	v_mul_f32_e32 v71, v71, v249
	v_mul_f32_e32 v72, v72, v250
	v_mul_f32_e32 v73, v73, v251
	v_cvt_pk_bf16_f32 v70, v70, v71
	v_cvt_pk_bf16_f32 v71, v72, v73
	s_waitcnt lgkmcnt(0)
	v_lshlrev_b32_e32 v244, 16, v238
	v_and_b32_e32 v245, 0xffff0000, v238
	v_lshlrev_b32_e32 v246, 16, v239
	v_and_b32_e32 v247, 0xffff0000, v239
	v_mul_f32_e32 v248, v178, v244
	v_mul_f32_e32 v249, v179, v245
	v_mul_f32_e32 v250, v180, v246
	v_mul_f32_e32 v251, v181, v247
	v_lshlrev_b32_e32 v244, 16, v240
	v_and_b32_e32 v245, 0xffff0000, v240
	v_lshlrev_b32_e32 v246, 16, v241
	v_and_b32_e32 v247, 0xffff0000, v241
	v_fmac_f32_e32 v248, v182, v244
	v_fmac_f32_e32 v249, v183, v245
	v_fmac_f32_e32 v250, v184, v246
	v_fmac_f32_e32 v251, v185, v247
	v_lshlrev_b32_e32 v244, 16, v242
	v_and_b32_e32 v245, 0xffff0000, v242
	v_lshlrev_b32_e32 v246, 16, v243
	v_and_b32_e32 v247, 0xffff0000, v243
	v_fmac_f32_e32 v248, v186, v244
	v_fmac_f32_e32 v249, v187, v245
	v_fmac_f32_e32 v250, v188, v246
	v_fmac_f32_e32 v251, v189, v247
	v_mul_f32_e32 v244, 0xbfb8aa3b, v248
	v_mul_f32_e32 v245, 0xbfb8aa3b, v249
	v_mul_f32_e32 v246, 0xbfb8aa3b, v250
	v_mul_f32_e32 v247, 0xbfb8aa3b, v251
	v_exp_f32_e32 v244, v244
	v_exp_f32_e32 v245, v245
	v_exp_f32_e32 v246, v246
	v_exp_f32_e32 v247, v247
	v_add_f32_e32 v244, 1.0, v244
	v_add_f32_e32 v245, 1.0, v245
	v_add_f32_e32 v246, 1.0, v246
	v_add_f32_e32 v247, 1.0, v247
	v_rcp_f32_e32 v244, v244
	v_rcp_f32_e32 v245, v245
	v_rcp_f32_e32 v246, v246
	v_rcp_f32_e32 v247, v247
	v_mul_f32_e32 v248, v248, v244
	v_mul_f32_e32 v249, v249, v245
	v_mul_f32_e32 v250, v250, v246
	v_mul_f32_e32 v251, v251, v247
	v_mul_f32_e32 v66, v66, v248
	v_mul_f32_e32 v67, v67, v249
	v_mul_f32_e32 v68, v68, v250
	v_mul_f32_e32 v69, v69, v251
	v_cvt_pk_bf16_f32 v66, v66, v67
	v_cvt_pk_bf16_f32 v67, v68, v69
	s_waitcnt vmcnt(0)
	s_barrier
	ds_read_b64 v[232:233], v198
	ds_read_b64 v[234:235], v200
	ds_read_b64 v[236:237], v202
	ds_read_b64 v[238:239], v199
	ds_read_b64 v[240:241], v201
	ds_read_b64 v[242:243], v203
	s_waitcnt lgkmcnt(3)
	v_lshlrev_b32_e32 v244, 16, v232
	v_and_b32_e32 v245, 0xffff0000, v232
	v_lshlrev_b32_e32 v246, 16, v233
	v_and_b32_e32 v247, 0xffff0000, v233
	v_mul_f32_e32 v248, v142, v244
	v_mul_f32_e32 v249, v143, v245
	v_mul_f32_e32 v250, v144, v246
	v_mul_f32_e32 v251, v145, v247
	v_lshlrev_b32_e32 v244, 16, v234
	v_and_b32_e32 v245, 0xffff0000, v234
	v_lshlrev_b32_e32 v246, 16, v235
	v_and_b32_e32 v247, 0xffff0000, v235
	v_fmac_f32_e32 v248, v146, v244
	v_fmac_f32_e32 v249, v147, v245
	v_fmac_f32_e32 v250, v148, v246
	v_fmac_f32_e32 v251, v149, v247
	v_lshlrev_b32_e32 v244, 16, v236
	v_and_b32_e32 v245, 0xffff0000, v236
	v_lshlrev_b32_e32 v246, 16, v237
	v_and_b32_e32 v247, 0xffff0000, v237
	v_fmac_f32_e32 v248, v150, v244
	v_fmac_f32_e32 v249, v151, v245
	v_fmac_f32_e32 v250, v152, v246
	v_fmac_f32_e32 v251, v153, v247
	v_mul_f32_e32 v244, 0xbfb8aa3b, v248
	v_mul_f32_e32 v245, 0xbfb8aa3b, v249
	v_mul_f32_e32 v246, 0xbfb8aa3b, v250
	v_mul_f32_e32 v247, 0xbfb8aa3b, v251
	v_exp_f32_e32 v244, v244
	v_exp_f32_e32 v245, v245
	v_exp_f32_e32 v246, v246
	v_exp_f32_e32 v247, v247
	v_add_f32_e32 v244, 1.0, v244
	v_add_f32_e32 v245, 1.0, v245
	v_add_f32_e32 v246, 1.0, v246
	v_add_f32_e32 v247, 1.0, v247
	v_rcp_f32_e32 v244, v244
	v_rcp_f32_e32 v245, v245
	v_rcp_f32_e32 v246, v246
	v_rcp_f32_e32 v247, v247
	v_mul_f32_e32 v248, v248, v244
	v_mul_f32_e32 v249, v249, v245
	v_mul_f32_e32 v250, v250, v246
	v_mul_f32_e32 v251, v251, v247
	v_mul_f32_e32 v62, v62, v248
	v_mul_f32_e32 v63, v63, v249
	v_mul_f32_e32 v64, v64, v250
	v_mul_f32_e32 v65, v65, v251
	v_cvt_pk_bf16_f32 v62, v62, v63
	v_cvt_pk_bf16_f32 v63, v64, v65
	ds_read_b64 v[232:233], v198 offset:256
	ds_read_b64 v[234:235], v200 offset:256
	ds_read_b64 v[236:237], v202 offset:256
	s_waitcnt lgkmcnt(3)
	v_lshlrev_b32_e32 v244, 16, v238
	v_and_b32_e32 v245, 0xffff0000, v238
	v_lshlrev_b32_e32 v246, 16, v239
	v_and_b32_e32 v247, 0xffff0000, v239
	v_mul_f32_e32 v248, v154, v244
	v_mul_f32_e32 v249, v155, v245
	v_mul_f32_e32 v250, v156, v246
	v_mul_f32_e32 v251, v157, v247
	v_lshlrev_b32_e32 v244, 16, v240
	v_and_b32_e32 v245, 0xffff0000, v240
	v_lshlrev_b32_e32 v246, 16, v241
	v_and_b32_e32 v247, 0xffff0000, v241
	v_fmac_f32_e32 v248, v158, v244
	v_fmac_f32_e32 v249, v159, v245
	v_fmac_f32_e32 v250, v160, v246
	v_fmac_f32_e32 v251, v161, v247
	v_lshlrev_b32_e32 v244, 16, v242
	v_and_b32_e32 v245, 0xffff0000, v242
	v_lshlrev_b32_e32 v246, 16, v243
	v_and_b32_e32 v247, 0xffff0000, v243
	v_fmac_f32_e32 v248, v162, v244
	v_fmac_f32_e32 v249, v163, v245
	v_fmac_f32_e32 v250, v164, v246
	v_fmac_f32_e32 v251, v165, v247
	v_mul_f32_e32 v244, 0xbfb8aa3b, v248
	v_mul_f32_e32 v245, 0xbfb8aa3b, v249
	v_mul_f32_e32 v246, 0xbfb8aa3b, v250
	v_mul_f32_e32 v247, 0xbfb8aa3b, v251
	v_exp_f32_e32 v244, v244
	v_exp_f32_e32 v245, v245
	v_exp_f32_e32 v246, v246
	v_exp_f32_e32 v247, v247
	v_add_f32_e32 v244, 1.0, v244
	v_add_f32_e32 v245, 1.0, v245
	v_add_f32_e32 v246, 1.0, v246
	v_add_f32_e32 v247, 1.0, v247
	v_rcp_f32_e32 v244, v244
	v_rcp_f32_e32 v245, v245
	v_rcp_f32_e32 v246, v246
	v_rcp_f32_e32 v247, v247
	v_mul_f32_e32 v248, v248, v244
	v_mul_f32_e32 v249, v249, v245
	v_mul_f32_e32 v250, v250, v246
	v_mul_f32_e32 v251, v251, v247
	v_mul_f32_e32 v58, v58, v248
	v_mul_f32_e32 v59, v59, v249
	v_mul_f32_e32 v60, v60, v250
	v_mul_f32_e32 v61, v61, v251
	v_cvt_pk_bf16_f32 v58, v58, v59
	v_cvt_pk_bf16_f32 v59, v60, v61
	ds_read_b64 v[238:239], v199 offset:256
	ds_read_b64 v[240:241], v201 offset:256
	ds_read_b64 v[242:243], v203 offset:256
	s_waitcnt lgkmcnt(3)
	v_lshlrev_b32_e32 v244, 16, v232
	v_and_b32_e32 v245, 0xffff0000, v232
	v_lshlrev_b32_e32 v246, 16, v233
	v_and_b32_e32 v247, 0xffff0000, v233
	v_mul_f32_e32 v248, v166, v244
	v_mul_f32_e32 v249, v167, v245
	v_mul_f32_e32 v250, v168, v246
	v_mul_f32_e32 v251, v169, v247
	v_lshlrev_b32_e32 v244, 16, v234
	v_and_b32_e32 v245, 0xffff0000, v234
	v_lshlrev_b32_e32 v246, 16, v235
	v_and_b32_e32 v247, 0xffff0000, v235
	v_fmac_f32_e32 v248, v170, v244
	v_fmac_f32_e32 v249, v171, v245
	v_fmac_f32_e32 v250, v172, v246
	v_fmac_f32_e32 v251, v173, v247
	v_lshlrev_b32_e32 v244, 16, v236
	v_and_b32_e32 v245, 0xffff0000, v236
	v_lshlrev_b32_e32 v246, 16, v237
	v_and_b32_e32 v247, 0xffff0000, v237
	v_fmac_f32_e32 v248, v174, v244
	v_fmac_f32_e32 v249, v175, v245
	v_fmac_f32_e32 v250, v176, v246
	v_fmac_f32_e32 v251, v177, v247
	v_mul_f32_e32 v244, 0xbfb8aa3b, v248
	v_mul_f32_e32 v245, 0xbfb8aa3b, v249
	v_mul_f32_e32 v246, 0xbfb8aa3b, v250
	v_mul_f32_e32 v247, 0xbfb8aa3b, v251
	v_exp_f32_e32 v244, v244
	v_exp_f32_e32 v245, v245
	v_exp_f32_e32 v246, v246
	v_exp_f32_e32 v247, v247
	v_add_f32_e32 v244, 1.0, v244
	v_add_f32_e32 v245, 1.0, v245
	v_add_f32_e32 v246, 1.0, v246
	v_add_f32_e32 v247, 1.0, v247
	v_rcp_f32_e32 v244, v244
	v_rcp_f32_e32 v245, v245
	v_rcp_f32_e32 v246, v246
	v_rcp_f32_e32 v247, v247
	v_mul_f32_e32 v248, v248, v244
	v_mul_f32_e32 v249, v249, v245
	v_mul_f32_e32 v250, v250, v246
	v_mul_f32_e32 v251, v251, v247
	v_mul_f32_e32 v54, v54, v248
	v_mul_f32_e32 v55, v55, v249
	v_mul_f32_e32 v56, v56, v250
	v_mul_f32_e32 v57, v57, v251
	v_cvt_pk_bf16_f32 v54, v54, v55
	v_cvt_pk_bf16_f32 v55, v56, v57
	ds_read_b64 v[232:233], v198 offset:8192
	ds_read_b64 v[234:235], v200 offset:8192
	ds_read_b64 v[236:237], v202 offset:8192
	s_waitcnt lgkmcnt(3)
	v_lshlrev_b32_e32 v244, 16, v238
	v_and_b32_e32 v245, 0xffff0000, v238
	v_lshlrev_b32_e32 v246, 16, v239
	v_and_b32_e32 v247, 0xffff0000, v239
	v_mul_f32_e32 v248, v178, v244
	v_mul_f32_e32 v249, v179, v245
	v_mul_f32_e32 v250, v180, v246
	v_mul_f32_e32 v251, v181, v247
	v_lshlrev_b32_e32 v244, 16, v240
	v_and_b32_e32 v245, 0xffff0000, v240
	v_lshlrev_b32_e32 v246, 16, v241
	v_and_b32_e32 v247, 0xffff0000, v241
	v_fmac_f32_e32 v248, v182, v244
	v_fmac_f32_e32 v249, v183, v245
	v_fmac_f32_e32 v250, v184, v246
	v_fmac_f32_e32 v251, v185, v247
	v_lshlrev_b32_e32 v244, 16, v242
	v_and_b32_e32 v245, 0xffff0000, v242
	v_lshlrev_b32_e32 v246, 16, v243
	v_and_b32_e32 v247, 0xffff0000, v243
	v_fmac_f32_e32 v248, v186, v244
	v_fmac_f32_e32 v249, v187, v245
	v_fmac_f32_e32 v250, v188, v246
	v_fmac_f32_e32 v251, v189, v247
	v_mul_f32_e32 v244, 0xbfb8aa3b, v248
	v_mul_f32_e32 v245, 0xbfb8aa3b, v249
	v_mul_f32_e32 v246, 0xbfb8aa3b, v250
	v_mul_f32_e32 v247, 0xbfb8aa3b, v251
	v_exp_f32_e32 v244, v244
	v_exp_f32_e32 v245, v245
	v_exp_f32_e32 v246, v246
	v_exp_f32_e32 v247, v247
	v_add_f32_e32 v244, 1.0, v244
	v_add_f32_e32 v245, 1.0, v245
	v_add_f32_e32 v246, 1.0, v246
	v_add_f32_e32 v247, 1.0, v247
	v_rcp_f32_e32 v244, v244
	v_rcp_f32_e32 v245, v245
	v_rcp_f32_e32 v246, v246
	v_rcp_f32_e32 v247, v247
	v_mul_f32_e32 v248, v248, v244
	v_mul_f32_e32 v249, v249, v245
	v_mul_f32_e32 v250, v250, v246
	v_mul_f32_e32 v251, v251, v247
	v_mul_f32_e32 v50, v50, v248
	v_mul_f32_e32 v51, v51, v249
	v_mul_f32_e32 v52, v52, v250
	v_mul_f32_e32 v53, v53, v251
	v_cvt_pk_bf16_f32 v50, v50, v51
	v_cvt_pk_bf16_f32 v51, v52, v53
	ds_read_b64 v[238:239], v199 offset:8192
	ds_read_b64 v[240:241], v201 offset:8192
	ds_read_b64 v[242:243], v203 offset:8192
	s_waitcnt lgkmcnt(3)
	v_lshlrev_b32_e32 v244, 16, v232
	v_and_b32_e32 v245, 0xffff0000, v232
	v_lshlrev_b32_e32 v246, 16, v233
	v_and_b32_e32 v247, 0xffff0000, v233
	v_mul_f32_e32 v248, v142, v244
	v_mul_f32_e32 v249, v143, v245
	v_mul_f32_e32 v250, v144, v246
	v_mul_f32_e32 v251, v145, v247
	v_lshlrev_b32_e32 v244, 16, v234
	v_and_b32_e32 v245, 0xffff0000, v234
	v_lshlrev_b32_e32 v246, 16, v235
	v_and_b32_e32 v247, 0xffff0000, v235
	v_fmac_f32_e32 v248, v146, v244
	v_fmac_f32_e32 v249, v147, v245
	v_fmac_f32_e32 v250, v148, v246
	v_fmac_f32_e32 v251, v149, v247
	v_lshlrev_b32_e32 v244, 16, v236
	v_and_b32_e32 v245, 0xffff0000, v236
	v_lshlrev_b32_e32 v246, 16, v237
	v_and_b32_e32 v247, 0xffff0000, v237
	v_fmac_f32_e32 v248, v150, v244
	v_fmac_f32_e32 v249, v151, v245
	v_fmac_f32_e32 v250, v152, v246
	v_fmac_f32_e32 v251, v153, v247
	v_mul_f32_e32 v244, 0xbfb8aa3b, v248
	v_mul_f32_e32 v245, 0xbfb8aa3b, v249
	v_mul_f32_e32 v246, 0xbfb8aa3b, v250
	v_mul_f32_e32 v247, 0xbfb8aa3b, v251
	v_exp_f32_e32 v244, v244
	v_exp_f32_e32 v245, v245
	v_exp_f32_e32 v246, v246
	v_exp_f32_e32 v247, v247
	v_add_f32_e32 v244, 1.0, v244
	v_add_f32_e32 v245, 1.0, v245
	v_add_f32_e32 v246, 1.0, v246
	v_add_f32_e32 v247, 1.0, v247
	v_rcp_f32_e32 v244, v244
	v_rcp_f32_e32 v245, v245
	v_rcp_f32_e32 v246, v246
	v_rcp_f32_e32 v247, v247
	v_mul_f32_e32 v248, v248, v244
	v_mul_f32_e32 v249, v249, v245
	v_mul_f32_e32 v250, v250, v246
	v_mul_f32_e32 v251, v251, v247
	v_mul_f32_e32 v46, v46, v248
	v_mul_f32_e32 v47, v47, v249
	v_mul_f32_e32 v48, v48, v250
	v_mul_f32_e32 v49, v49, v251
	v_cvt_pk_bf16_f32 v46, v46, v47
	v_cvt_pk_bf16_f32 v47, v48, v49
	ds_read_b64 v[232:233], v198 offset:8448
	ds_read_b64 v[234:235], v200 offset:8448
	ds_read_b64 v[236:237], v202 offset:8448
	s_waitcnt lgkmcnt(3)
	v_lshlrev_b32_e32 v244, 16, v238
	v_and_b32_e32 v245, 0xffff0000, v238
	v_lshlrev_b32_e32 v246, 16, v239
	v_and_b32_e32 v247, 0xffff0000, v239
	v_mul_f32_e32 v248, v154, v244
	v_mul_f32_e32 v249, v155, v245
	v_mul_f32_e32 v250, v156, v246
	v_mul_f32_e32 v251, v157, v247
	v_lshlrev_b32_e32 v244, 16, v240
	v_and_b32_e32 v245, 0xffff0000, v240
	v_lshlrev_b32_e32 v246, 16, v241
	v_and_b32_e32 v247, 0xffff0000, v241
	v_fmac_f32_e32 v248, v158, v244
	v_fmac_f32_e32 v249, v159, v245
	v_fmac_f32_e32 v250, v160, v246
	v_fmac_f32_e32 v251, v161, v247
	v_lshlrev_b32_e32 v244, 16, v242
	v_and_b32_e32 v245, 0xffff0000, v242
	v_lshlrev_b32_e32 v246, 16, v243
	v_and_b32_e32 v247, 0xffff0000, v243
	v_fmac_f32_e32 v248, v162, v244
	v_fmac_f32_e32 v249, v163, v245
	v_fmac_f32_e32 v250, v164, v246
	v_fmac_f32_e32 v251, v165, v247
	v_mul_f32_e32 v244, 0xbfb8aa3b, v248
	v_mul_f32_e32 v245, 0xbfb8aa3b, v249
	v_mul_f32_e32 v246, 0xbfb8aa3b, v250
	v_mul_f32_e32 v247, 0xbfb8aa3b, v251
	v_exp_f32_e32 v244, v244
	v_exp_f32_e32 v245, v245
	v_exp_f32_e32 v246, v246
	v_exp_f32_e32 v247, v247
	v_add_f32_e32 v244, 1.0, v244
	v_add_f32_e32 v245, 1.0, v245
	v_add_f32_e32 v246, 1.0, v246
	v_add_f32_e32 v247, 1.0, v247
	v_rcp_f32_e32 v244, v244
	v_rcp_f32_e32 v245, v245
	v_rcp_f32_e32 v246, v246
	v_rcp_f32_e32 v247, v247
	v_mul_f32_e32 v248, v248, v244
	v_mul_f32_e32 v249, v249, v245
	v_mul_f32_e32 v250, v250, v246
	v_mul_f32_e32 v251, v251, v247
	v_mul_f32_e32 v42, v42, v248
	v_mul_f32_e32 v43, v43, v249
	v_mul_f32_e32 v44, v44, v250
	v_mul_f32_e32 v45, v45, v251
	v_cvt_pk_bf16_f32 v42, v42, v43
	v_cvt_pk_bf16_f32 v43, v44, v45
	ds_read_b64 v[238:239], v199 offset:8448
	ds_read_b64 v[240:241], v201 offset:8448
	ds_read_b64 v[242:243], v203 offset:8448
	s_waitcnt lgkmcnt(3)
	v_lshlrev_b32_e32 v244, 16, v232
	v_and_b32_e32 v245, 0xffff0000, v232
	v_lshlrev_b32_e32 v246, 16, v233
	v_and_b32_e32 v247, 0xffff0000, v233
	v_mul_f32_e32 v248, v166, v244
	v_mul_f32_e32 v249, v167, v245
	v_mul_f32_e32 v250, v168, v246
	v_mul_f32_e32 v251, v169, v247
	v_lshlrev_b32_e32 v244, 16, v234
	v_and_b32_e32 v245, 0xffff0000, v234
	v_lshlrev_b32_e32 v246, 16, v235
	v_and_b32_e32 v247, 0xffff0000, v235
	v_fmac_f32_e32 v248, v170, v244
	v_fmac_f32_e32 v249, v171, v245
	v_fmac_f32_e32 v250, v172, v246
	v_fmac_f32_e32 v251, v173, v247
	v_lshlrev_b32_e32 v244, 16, v236
	v_and_b32_e32 v245, 0xffff0000, v236
	v_lshlrev_b32_e32 v246, 16, v237
	v_and_b32_e32 v247, 0xffff0000, v237
	v_fmac_f32_e32 v248, v174, v244
	v_fmac_f32_e32 v249, v175, v245
	v_fmac_f32_e32 v250, v176, v246
	v_fmac_f32_e32 v251, v177, v247
	v_mul_f32_e32 v244, 0xbfb8aa3b, v248
	v_mul_f32_e32 v245, 0xbfb8aa3b, v249
	v_mul_f32_e32 v246, 0xbfb8aa3b, v250
	v_mul_f32_e32 v247, 0xbfb8aa3b, v251
	v_exp_f32_e32 v244, v244
	v_exp_f32_e32 v245, v245
	v_exp_f32_e32 v246, v246
	v_exp_f32_e32 v247, v247
	v_add_f32_e32 v244, 1.0, v244
	v_add_f32_e32 v245, 1.0, v245
	v_add_f32_e32 v246, 1.0, v246
	v_add_f32_e32 v247, 1.0, v247
	v_rcp_f32_e32 v244, v244
	v_rcp_f32_e32 v245, v245
	v_rcp_f32_e32 v246, v246
	v_rcp_f32_e32 v247, v247
	v_mul_f32_e32 v248, v248, v244
	v_mul_f32_e32 v249, v249, v245
	v_mul_f32_e32 v250, v250, v246
	v_mul_f32_e32 v251, v251, v247
	v_mul_f32_e32 v38, v38, v248
	v_mul_f32_e32 v39, v39, v249
	v_mul_f32_e32 v40, v40, v250
	v_mul_f32_e32 v41, v41, v251
	v_cvt_pk_bf16_f32 v38, v38, v39
	v_cvt_pk_bf16_f32 v39, v40, v41
	ds_read_b64 v[232:233], v198 offset:16384
	ds_read_b64 v[234:235], v200 offset:16384
	ds_read_b64 v[236:237], v202 offset:16384
	s_waitcnt lgkmcnt(3)
	v_lshlrev_b32_e32 v244, 16, v238
	v_and_b32_e32 v245, 0xffff0000, v238
	v_lshlrev_b32_e32 v246, 16, v239
	v_and_b32_e32 v247, 0xffff0000, v239
	v_mul_f32_e32 v248, v178, v244
	v_mul_f32_e32 v249, v179, v245
	v_mul_f32_e32 v250, v180, v246
	v_mul_f32_e32 v251, v181, v247
	v_lshlrev_b32_e32 v244, 16, v240
	v_and_b32_e32 v245, 0xffff0000, v240
	v_lshlrev_b32_e32 v246, 16, v241
	v_and_b32_e32 v247, 0xffff0000, v241
	v_fmac_f32_e32 v248, v182, v244
	v_fmac_f32_e32 v249, v183, v245
	v_fmac_f32_e32 v250, v184, v246
	v_fmac_f32_e32 v251, v185, v247
	v_lshlrev_b32_e32 v244, 16, v242
	v_and_b32_e32 v245, 0xffff0000, v242
	v_lshlrev_b32_e32 v246, 16, v243
	v_and_b32_e32 v247, 0xffff0000, v243
	v_fmac_f32_e32 v248, v186, v244
	v_fmac_f32_e32 v249, v187, v245
	v_fmac_f32_e32 v250, v188, v246
	v_fmac_f32_e32 v251, v189, v247
	v_mul_f32_e32 v244, 0xbfb8aa3b, v248
	v_mul_f32_e32 v245, 0xbfb8aa3b, v249
	v_mul_f32_e32 v246, 0xbfb8aa3b, v250
	v_mul_f32_e32 v247, 0xbfb8aa3b, v251
	v_exp_f32_e32 v244, v244
	v_exp_f32_e32 v245, v245
	v_exp_f32_e32 v246, v246
	v_exp_f32_e32 v247, v247
	v_add_f32_e32 v244, 1.0, v244
	v_add_f32_e32 v245, 1.0, v245
	v_add_f32_e32 v246, 1.0, v246
	v_add_f32_e32 v247, 1.0, v247
	v_rcp_f32_e32 v244, v244
	v_rcp_f32_e32 v245, v245
	v_rcp_f32_e32 v246, v246
	v_rcp_f32_e32 v247, v247
	v_mul_f32_e32 v248, v248, v244
	v_mul_f32_e32 v249, v249, v245
	v_mul_f32_e32 v250, v250, v246
	v_mul_f32_e32 v251, v251, v247
	v_mul_f32_e32 v34, v34, v248
	v_mul_f32_e32 v35, v35, v249
	v_mul_f32_e32 v36, v36, v250
	v_mul_f32_e32 v37, v37, v251
	v_cvt_pk_bf16_f32 v34, v34, v35
	v_cvt_pk_bf16_f32 v35, v36, v37
	ds_read_b64 v[238:239], v199 offset:16384
	ds_read_b64 v[240:241], v201 offset:16384
	ds_read_b64 v[242:243], v203 offset:16384
	s_waitcnt lgkmcnt(3)
	v_lshlrev_b32_e32 v244, 16, v232
	v_and_b32_e32 v245, 0xffff0000, v232
	v_lshlrev_b32_e32 v246, 16, v233
	v_and_b32_e32 v247, 0xffff0000, v233
	v_mul_f32_e32 v248, v142, v244
	v_mul_f32_e32 v249, v143, v245
	v_mul_f32_e32 v250, v144, v246
	v_mul_f32_e32 v251, v145, v247
	v_lshlrev_b32_e32 v244, 16, v234
	v_and_b32_e32 v245, 0xffff0000, v234
	v_lshlrev_b32_e32 v246, 16, v235
	v_and_b32_e32 v247, 0xffff0000, v235
	v_fmac_f32_e32 v248, v146, v244
	v_fmac_f32_e32 v249, v147, v245
	v_fmac_f32_e32 v250, v148, v246
	v_fmac_f32_e32 v251, v149, v247
	v_lshlrev_b32_e32 v244, 16, v236
	v_and_b32_e32 v245, 0xffff0000, v236
	v_lshlrev_b32_e32 v246, 16, v237
	v_and_b32_e32 v247, 0xffff0000, v237
	v_fmac_f32_e32 v248, v150, v244
	v_fmac_f32_e32 v249, v151, v245
	v_fmac_f32_e32 v250, v152, v246
	v_fmac_f32_e32 v251, v153, v247
	v_mul_f32_e32 v244, 0xbfb8aa3b, v248
	v_mul_f32_e32 v245, 0xbfb8aa3b, v249
	v_mul_f32_e32 v246, 0xbfb8aa3b, v250
	v_mul_f32_e32 v247, 0xbfb8aa3b, v251
	v_exp_f32_e32 v244, v244
	v_exp_f32_e32 v245, v245
	v_exp_f32_e32 v246, v246
	v_exp_f32_e32 v247, v247
	v_add_f32_e32 v244, 1.0, v244
	v_add_f32_e32 v245, 1.0, v245
	v_add_f32_e32 v246, 1.0, v246
	v_add_f32_e32 v247, 1.0, v247
	v_rcp_f32_e32 v244, v244
	v_rcp_f32_e32 v245, v245
	v_rcp_f32_e32 v246, v246
	v_rcp_f32_e32 v247, v247
	v_mul_f32_e32 v248, v248, v244
	v_mul_f32_e32 v249, v249, v245
	v_mul_f32_e32 v250, v250, v246
	v_mul_f32_e32 v251, v251, v247
	v_mul_f32_e32 v30, v30, v248
	v_mul_f32_e32 v31, v31, v249
	v_mul_f32_e32 v32, v32, v250
	v_mul_f32_e32 v33, v33, v251
	v_cvt_pk_bf16_f32 v30, v30, v31
	v_cvt_pk_bf16_f32 v31, v32, v33
	ds_read_b64 v[232:233], v198 offset:16640
	ds_read_b64 v[234:235], v200 offset:16640
	ds_read_b64 v[236:237], v202 offset:16640
	s_waitcnt lgkmcnt(3)
	v_lshlrev_b32_e32 v244, 16, v238
	v_and_b32_e32 v245, 0xffff0000, v238
	v_lshlrev_b32_e32 v246, 16, v239
	v_and_b32_e32 v247, 0xffff0000, v239
	v_mul_f32_e32 v248, v154, v244
	v_mul_f32_e32 v249, v155, v245
	v_mul_f32_e32 v250, v156, v246
	v_mul_f32_e32 v251, v157, v247
	v_lshlrev_b32_e32 v244, 16, v240
	v_and_b32_e32 v245, 0xffff0000, v240
	v_lshlrev_b32_e32 v246, 16, v241
	v_and_b32_e32 v247, 0xffff0000, v241
	v_fmac_f32_e32 v248, v158, v244
	v_fmac_f32_e32 v249, v159, v245
	v_fmac_f32_e32 v250, v160, v246
	v_fmac_f32_e32 v251, v161, v247
	v_lshlrev_b32_e32 v244, 16, v242
	v_and_b32_e32 v245, 0xffff0000, v242
	v_lshlrev_b32_e32 v246, 16, v243
	v_and_b32_e32 v247, 0xffff0000, v243
	v_fmac_f32_e32 v248, v162, v244
	v_fmac_f32_e32 v249, v163, v245
	v_fmac_f32_e32 v250, v164, v246
	v_fmac_f32_e32 v251, v165, v247
	v_mul_f32_e32 v244, 0xbfb8aa3b, v248
	v_mul_f32_e32 v245, 0xbfb8aa3b, v249
	v_mul_f32_e32 v246, 0xbfb8aa3b, v250
	v_mul_f32_e32 v247, 0xbfb8aa3b, v251
	v_exp_f32_e32 v244, v244
	v_exp_f32_e32 v245, v245
	v_exp_f32_e32 v246, v246
	v_exp_f32_e32 v247, v247
	v_add_f32_e32 v244, 1.0, v244
	v_add_f32_e32 v245, 1.0, v245
	v_add_f32_e32 v246, 1.0, v246
	v_add_f32_e32 v247, 1.0, v247
	v_rcp_f32_e32 v244, v244
	v_rcp_f32_e32 v245, v245
	v_rcp_f32_e32 v246, v246
	v_rcp_f32_e32 v247, v247
	v_mul_f32_e32 v248, v248, v244
	v_mul_f32_e32 v249, v249, v245
	v_mul_f32_e32 v250, v250, v246
	v_mul_f32_e32 v251, v251, v247
	v_mul_f32_e32 v26, v26, v248
	v_mul_f32_e32 v27, v27, v249
	v_mul_f32_e32 v28, v28, v250
	v_mul_f32_e32 v29, v29, v251
	v_cvt_pk_bf16_f32 v26, v26, v27
	v_cvt_pk_bf16_f32 v27, v28, v29
	ds_read_b64 v[238:239], v199 offset:16640
	ds_read_b64 v[240:241], v201 offset:16640
	ds_read_b64 v[242:243], v203 offset:16640
	s_waitcnt lgkmcnt(3)
	v_lshlrev_b32_e32 v244, 16, v232
	v_and_b32_e32 v245, 0xffff0000, v232
	v_lshlrev_b32_e32 v246, 16, v233
	v_and_b32_e32 v247, 0xffff0000, v233
	v_mul_f32_e32 v248, v166, v244
	v_mul_f32_e32 v249, v167, v245
	v_mul_f32_e32 v250, v168, v246
	v_mul_f32_e32 v251, v169, v247
	v_lshlrev_b32_e32 v244, 16, v234
	v_and_b32_e32 v245, 0xffff0000, v234
	v_lshlrev_b32_e32 v246, 16, v235
	v_and_b32_e32 v247, 0xffff0000, v235
	v_fmac_f32_e32 v248, v170, v244
	v_fmac_f32_e32 v249, v171, v245
	v_fmac_f32_e32 v250, v172, v246
	v_fmac_f32_e32 v251, v173, v247
	v_lshlrev_b32_e32 v244, 16, v236
	v_and_b32_e32 v245, 0xffff0000, v236
	v_lshlrev_b32_e32 v246, 16, v237
	v_and_b32_e32 v247, 0xffff0000, v237
	v_fmac_f32_e32 v248, v174, v244
	v_fmac_f32_e32 v249, v175, v245
	v_fmac_f32_e32 v250, v176, v246
	v_fmac_f32_e32 v251, v177, v247
	v_mul_f32_e32 v244, 0xbfb8aa3b, v248
	v_mul_f32_e32 v245, 0xbfb8aa3b, v249
	v_mul_f32_e32 v246, 0xbfb8aa3b, v250
	v_mul_f32_e32 v247, 0xbfb8aa3b, v251
	v_exp_f32_e32 v244, v244
	v_exp_f32_e32 v245, v245
	v_exp_f32_e32 v246, v246
	v_exp_f32_e32 v247, v247
	v_add_f32_e32 v244, 1.0, v244
	v_add_f32_e32 v245, 1.0, v245
	v_add_f32_e32 v246, 1.0, v246
	v_add_f32_e32 v247, 1.0, v247
	v_rcp_f32_e32 v244, v244
	v_rcp_f32_e32 v245, v245
	v_rcp_f32_e32 v246, v246
	v_rcp_f32_e32 v247, v247
	v_mul_f32_e32 v248, v248, v244
	v_mul_f32_e32 v249, v249, v245
	v_mul_f32_e32 v250, v250, v246
	v_mul_f32_e32 v251, v251, v247
	v_mul_f32_e32 v22, v22, v248
	v_mul_f32_e32 v23, v23, v249
	v_mul_f32_e32 v24, v24, v250
	v_mul_f32_e32 v25, v25, v251
	v_cvt_pk_bf16_f32 v22, v22, v23
	v_cvt_pk_bf16_f32 v23, v24, v25
	ds_read_b64 v[232:233], v198 offset:24576
	ds_read_b64 v[234:235], v200 offset:24576
	ds_read_b64 v[236:237], v204
	s_waitcnt lgkmcnt(3)
	v_lshlrev_b32_e32 v244, 16, v238
	v_and_b32_e32 v245, 0xffff0000, v238
	v_lshlrev_b32_e32 v246, 16, v239
	v_and_b32_e32 v247, 0xffff0000, v239
	v_mul_f32_e32 v248, v178, v244
	v_mul_f32_e32 v249, v179, v245
	v_mul_f32_e32 v250, v180, v246
	v_mul_f32_e32 v251, v181, v247
	v_lshlrev_b32_e32 v244, 16, v240
	v_and_b32_e32 v245, 0xffff0000, v240
	v_lshlrev_b32_e32 v246, 16, v241
	v_and_b32_e32 v247, 0xffff0000, v241
	v_fmac_f32_e32 v248, v182, v244
	v_fmac_f32_e32 v249, v183, v245
	v_fmac_f32_e32 v250, v184, v246
	v_fmac_f32_e32 v251, v185, v247
	v_lshlrev_b32_e32 v244, 16, v242
	v_and_b32_e32 v245, 0xffff0000, v242
	v_lshlrev_b32_e32 v246, 16, v243
	v_and_b32_e32 v247, 0xffff0000, v243
	v_fmac_f32_e32 v248, v186, v244
	v_fmac_f32_e32 v249, v187, v245
	v_fmac_f32_e32 v250, v188, v246
	v_fmac_f32_e32 v251, v189, v247
	v_mul_f32_e32 v244, 0xbfb8aa3b, v248
	v_mul_f32_e32 v245, 0xbfb8aa3b, v249
	v_mul_f32_e32 v246, 0xbfb8aa3b, v250
	v_mul_f32_e32 v247, 0xbfb8aa3b, v251
	v_exp_f32_e32 v244, v244
	v_exp_f32_e32 v245, v245
	v_exp_f32_e32 v246, v246
	v_exp_f32_e32 v247, v247
	v_add_f32_e32 v244, 1.0, v244
	v_add_f32_e32 v245, 1.0, v245
	v_add_f32_e32 v246, 1.0, v246
	v_add_f32_e32 v247, 1.0, v247
	v_rcp_f32_e32 v244, v244
	v_rcp_f32_e32 v245, v245
	v_rcp_f32_e32 v246, v246
	v_rcp_f32_e32 v247, v247
	v_mul_f32_e32 v248, v248, v244
	v_mul_f32_e32 v249, v249, v245
	v_mul_f32_e32 v250, v250, v246
	v_mul_f32_e32 v251, v251, v247
	v_mul_f32_e32 v18, v18, v248
	v_mul_f32_e32 v19, v19, v249
	v_mul_f32_e32 v20, v20, v250
	v_mul_f32_e32 v21, v21, v251
	v_cvt_pk_bf16_f32 v18, v18, v19
	v_cvt_pk_bf16_f32 v19, v20, v21
	ds_read_b64 v[238:239], v199 offset:24576
	ds_read_b64 v[240:241], v201 offset:24576
	ds_read_b64 v[242:243], v205
	s_waitcnt lgkmcnt(3)
	v_lshlrev_b32_e32 v244, 16, v232
	v_and_b32_e32 v245, 0xffff0000, v232
	v_lshlrev_b32_e32 v246, 16, v233
	v_and_b32_e32 v247, 0xffff0000, v233
	v_mul_f32_e32 v248, v142, v244
	v_mul_f32_e32 v249, v143, v245
	v_mul_f32_e32 v250, v144, v246
	v_mul_f32_e32 v251, v145, v247
	v_lshlrev_b32_e32 v244, 16, v234
	v_and_b32_e32 v245, 0xffff0000, v234
	v_lshlrev_b32_e32 v246, 16, v235
	v_and_b32_e32 v247, 0xffff0000, v235
	v_fmac_f32_e32 v248, v146, v244
	v_fmac_f32_e32 v249, v147, v245
	v_fmac_f32_e32 v250, v148, v246
	v_fmac_f32_e32 v251, v149, v247
	v_lshlrev_b32_e32 v244, 16, v236
	v_and_b32_e32 v245, 0xffff0000, v236
	v_lshlrev_b32_e32 v246, 16, v237
	v_and_b32_e32 v247, 0xffff0000, v237
	v_fmac_f32_e32 v248, v150, v244
	v_fmac_f32_e32 v249, v151, v245
	v_fmac_f32_e32 v250, v152, v246
	v_fmac_f32_e32 v251, v153, v247
	v_mul_f32_e32 v244, 0xbfb8aa3b, v248
	v_mul_f32_e32 v245, 0xbfb8aa3b, v249
	v_mul_f32_e32 v246, 0xbfb8aa3b, v250
	v_mul_f32_e32 v247, 0xbfb8aa3b, v251
	v_exp_f32_e32 v244, v244
	v_exp_f32_e32 v245, v245
	v_exp_f32_e32 v246, v246
	v_exp_f32_e32 v247, v247
	v_add_f32_e32 v244, 1.0, v244
	v_add_f32_e32 v245, 1.0, v245
	v_add_f32_e32 v246, 1.0, v246
	v_add_f32_e32 v247, 1.0, v247
	v_rcp_f32_e32 v244, v244
	v_rcp_f32_e32 v245, v245
	v_rcp_f32_e32 v246, v246
	v_rcp_f32_e32 v247, v247
	v_mul_f32_e32 v248, v248, v244
	v_mul_f32_e32 v249, v249, v245
	v_mul_f32_e32 v250, v250, v246
	v_mul_f32_e32 v251, v251, v247
	v_mul_f32_e32 v14, v14, v248
	v_mul_f32_e32 v15, v15, v249
	v_mul_f32_e32 v16, v16, v250
	v_mul_f32_e32 v17, v17, v251
	v_cvt_pk_bf16_f32 v14, v14, v15
	v_cvt_pk_bf16_f32 v15, v16, v17
	ds_read_b64 v[232:233], v198 offset:24832
	ds_read_b64 v[234:235], v200 offset:24832
	ds_read_b64 v[236:237], v204 offset:256
	s_waitcnt lgkmcnt(3)
	v_lshlrev_b32_e32 v244, 16, v238
	v_and_b32_e32 v245, 0xffff0000, v238
	v_lshlrev_b32_e32 v246, 16, v239
	v_and_b32_e32 v247, 0xffff0000, v239
	v_mul_f32_e32 v248, v154, v244
	v_mul_f32_e32 v249, v155, v245
	v_mul_f32_e32 v250, v156, v246
	v_mul_f32_e32 v251, v157, v247
	v_lshlrev_b32_e32 v244, 16, v240
	v_and_b32_e32 v245, 0xffff0000, v240
	v_lshlrev_b32_e32 v246, 16, v241
	v_and_b32_e32 v247, 0xffff0000, v241
	v_fmac_f32_e32 v248, v158, v244
	v_fmac_f32_e32 v249, v159, v245
	v_fmac_f32_e32 v250, v160, v246
	v_fmac_f32_e32 v251, v161, v247
	v_lshlrev_b32_e32 v244, 16, v242
	v_and_b32_e32 v245, 0xffff0000, v242
	v_lshlrev_b32_e32 v246, 16, v243
	v_and_b32_e32 v247, 0xffff0000, v243
	v_fmac_f32_e32 v248, v162, v244
	v_fmac_f32_e32 v249, v163, v245
	v_fmac_f32_e32 v250, v164, v246
	v_fmac_f32_e32 v251, v165, v247
	v_mul_f32_e32 v244, 0xbfb8aa3b, v248
	v_mul_f32_e32 v245, 0xbfb8aa3b, v249
	v_mul_f32_e32 v246, 0xbfb8aa3b, v250
	v_mul_f32_e32 v247, 0xbfb8aa3b, v251
	v_exp_f32_e32 v244, v244
	v_exp_f32_e32 v245, v245
	v_exp_f32_e32 v246, v246
	v_exp_f32_e32 v247, v247
	v_add_f32_e32 v244, 1.0, v244
	v_add_f32_e32 v245, 1.0, v245
	v_add_f32_e32 v246, 1.0, v246
	v_add_f32_e32 v247, 1.0, v247
	v_rcp_f32_e32 v244, v244
	v_rcp_f32_e32 v245, v245
	v_rcp_f32_e32 v246, v246
	v_rcp_f32_e32 v247, v247
	v_mul_f32_e32 v248, v248, v244
	v_mul_f32_e32 v249, v249, v245
	v_mul_f32_e32 v250, v250, v246
	v_mul_f32_e32 v251, v251, v247
	v_mul_f32_e32 v10, v10, v248
	v_mul_f32_e32 v11, v11, v249
	v_mul_f32_e32 v12, v12, v250
	v_mul_f32_e32 v13, v13, v251
	v_cvt_pk_bf16_f32 v10, v10, v11
	v_cvt_pk_bf16_f32 v11, v12, v13
	ds_read_b64 v[238:239], v199 offset:24832
	ds_read_b64 v[240:241], v201 offset:24832
	ds_read_b64 v[242:243], v205 offset:256
	s_waitcnt lgkmcnt(3)
	v_lshlrev_b32_e32 v244, 16, v232
	v_and_b32_e32 v245, 0xffff0000, v232
	v_lshlrev_b32_e32 v246, 16, v233
	v_and_b32_e32 v247, 0xffff0000, v233
	v_mul_f32_e32 v248, v166, v244
	v_mul_f32_e32 v249, v167, v245
	v_mul_f32_e32 v250, v168, v246
	v_mul_f32_e32 v251, v169, v247
	v_lshlrev_b32_e32 v244, 16, v234
	v_and_b32_e32 v245, 0xffff0000, v234
	v_lshlrev_b32_e32 v246, 16, v235
	v_and_b32_e32 v247, 0xffff0000, v235
	v_fmac_f32_e32 v248, v170, v244
	v_fmac_f32_e32 v249, v171, v245
	v_fmac_f32_e32 v250, v172, v246
	v_fmac_f32_e32 v251, v173, v247
	v_lshlrev_b32_e32 v244, 16, v236
	v_and_b32_e32 v245, 0xffff0000, v236
	v_lshlrev_b32_e32 v246, 16, v237
	v_and_b32_e32 v247, 0xffff0000, v237
	v_fmac_f32_e32 v248, v174, v244
	v_fmac_f32_e32 v249, v175, v245
	v_fmac_f32_e32 v250, v176, v246
	v_fmac_f32_e32 v251, v177, v247
	v_mul_f32_e32 v244, 0xbfb8aa3b, v248
	v_mul_f32_e32 v245, 0xbfb8aa3b, v249
	v_mul_f32_e32 v246, 0xbfb8aa3b, v250
	v_mul_f32_e32 v247, 0xbfb8aa3b, v251
	v_exp_f32_e32 v244, v244
	v_exp_f32_e32 v245, v245
	v_exp_f32_e32 v246, v246
	v_exp_f32_e32 v247, v247
	v_add_f32_e32 v244, 1.0, v244
	v_add_f32_e32 v245, 1.0, v245
	v_add_f32_e32 v246, 1.0, v246
	v_add_f32_e32 v247, 1.0, v247
	v_rcp_f32_e32 v244, v244
	v_rcp_f32_e32 v245, v245
	v_rcp_f32_e32 v246, v246
	v_rcp_f32_e32 v247, v247
	v_mul_f32_e32 v248, v248, v244
	v_mul_f32_e32 v249, v249, v245
	v_mul_f32_e32 v250, v250, v246
	v_mul_f32_e32 v251, v251, v247
	v_mul_f32_e32 v6, v6, v248
	v_mul_f32_e32 v7, v7, v249
	v_mul_f32_e32 v8, v8, v250
	v_mul_f32_e32 v9, v9, v251
	v_cvt_pk_bf16_f32 v6, v6, v7
	v_cvt_pk_bf16_f32 v7, v8, v9
	s_waitcnt lgkmcnt(0)
	v_lshlrev_b32_e32 v244, 16, v238
	v_and_b32_e32 v245, 0xffff0000, v238
	v_lshlrev_b32_e32 v246, 16, v239
	v_and_b32_e32 v247, 0xffff0000, v239
	v_mul_f32_e32 v248, v178, v244
	v_mul_f32_e32 v249, v179, v245
	v_mul_f32_e32 v250, v180, v246
	v_mul_f32_e32 v251, v181, v247
	v_lshlrev_b32_e32 v244, 16, v240
	v_and_b32_e32 v245, 0xffff0000, v240
	v_lshlrev_b32_e32 v246, 16, v241
	v_and_b32_e32 v247, 0xffff0000, v241
	v_fmac_f32_e32 v248, v182, v244
	v_fmac_f32_e32 v249, v183, v245
	v_fmac_f32_e32 v250, v184, v246
	v_fmac_f32_e32 v251, v185, v247
	v_lshlrev_b32_e32 v244, 16, v242
	v_and_b32_e32 v245, 0xffff0000, v242
	v_lshlrev_b32_e32 v246, 16, v243
	v_and_b32_e32 v247, 0xffff0000, v243
	v_fmac_f32_e32 v248, v186, v244
	v_fmac_f32_e32 v249, v187, v245
	v_fmac_f32_e32 v250, v188, v246
	v_fmac_f32_e32 v251, v189, v247
	v_mul_f32_e32 v244, 0xbfb8aa3b, v248
	v_mul_f32_e32 v245, 0xbfb8aa3b, v249
	v_mul_f32_e32 v246, 0xbfb8aa3b, v250
	v_mul_f32_e32 v247, 0xbfb8aa3b, v251
	v_exp_f32_e32 v244, v244
	v_exp_f32_e32 v245, v245
	v_exp_f32_e32 v246, v246
	v_exp_f32_e32 v247, v247
	v_add_f32_e32 v244, 1.0, v244
	v_add_f32_e32 v245, 1.0, v245
	v_add_f32_e32 v246, 1.0, v246
	v_add_f32_e32 v247, 1.0, v247
	v_rcp_f32_e32 v244, v244
	v_rcp_f32_e32 v245, v245
	v_rcp_f32_e32 v246, v246
	v_rcp_f32_e32 v247, v247
	v_mul_f32_e32 v248, v248, v244
	v_mul_f32_e32 v249, v249, v245
	v_mul_f32_e32 v250, v250, v246
	v_mul_f32_e32 v251, v251, v247
	v_mul_f32_e32 v2, v2, v248
	v_mul_f32_e32 v3, v3, v249
	v_mul_f32_e32 v4, v4, v250
	v_mul_f32_e32 v5, v5, v251
	v_cvt_pk_bf16_f32 v2, v2, v3
	v_cvt_pk_bf16_f32 v3, v4, v5
	v_lshrrev_b32_e32 v132, 1, v129
	v_lshl_add_u32 v132, v130, 2, v132
	v_and_b32_e32 v133, 1, v129
	v_lshlrev_b32_e32 v133, 3, v133
	v_lshl_add_u32 v134, v131, 6, v128
	v_lshlrev_b32_e32 v135, 9, v134
	v_add_u32_e32 v135, v135, v133
	v_mov_b32_e32 v136, v132
	v_xor_b32_e32 v136, v136, v128
	v_lshl_add_u32 v190, v136, 4, v135
	v_add_u32_e32 v192, 0x10000, v190
	v_add_u32_e32 v136, 2, v132
	v_xor_b32_e32 v136, v136, v128
	v_lshl_add_u32 v191, v136, 4, v135
	v_add_u32_e32 v193, 0x10000, v191
	s_waitcnt lgkmcnt(0)
	s_barrier
	ds_write_b64 v190, v[138:139]
	ds_write_b64 v191, v[122:123]
	ds_write_b64 v190, v[118:119] offset:256
	ds_write_b64 v191, v[114:115] offset:256
	ds_write_b64 v190, v[110:111] offset:8192
	ds_write_b64 v191, v[106:107] offset:8192
	ds_write_b64 v190, v[102:103] offset:8448
	ds_write_b64 v191, v[98:99] offset:8448
	ds_write_b64 v190, v[94:95] offset:16384
	ds_write_b64 v191, v[90:91] offset:16384
	ds_write_b64 v190, v[86:87] offset:16640
	ds_write_b64 v191, v[82:83] offset:16640
	ds_write_b64 v190, v[78:79] offset:24576
	ds_write_b64 v191, v[74:75] offset:24576
	ds_write_b64 v190, v[70:71] offset:24832
	ds_write_b64 v191, v[66:67] offset:24832
	ds_write_b64 v192, v[62:63]
	ds_write_b64 v193, v[58:59]
	ds_write_b64 v192, v[54:55] offset:256
	ds_write_b64 v193, v[50:51] offset:256
	ds_write_b64 v192, v[46:47] offset:8192
	ds_write_b64 v193, v[42:43] offset:8192
	ds_write_b64 v192, v[38:39] offset:8448
	ds_write_b64 v193, v[34:35] offset:8448
	ds_write_b64 v192, v[30:31] offset:16384
	ds_write_b64 v193, v[26:27] offset:16384
	ds_write_b64 v192, v[22:23] offset:16640
	ds_write_b64 v193, v[18:19] offset:16640
	ds_write_b64 v192, v[14:15] offset:24576
	ds_write_b64 v193, v[10:11] offset:24576
	ds_write_b64 v192, v[6:7] offset:24832
	ds_write_b64 v193, v[2:3] offset:24832
	v_lshlrev_b32_e32 v194, 4, v126
	v_lshl_add_u32 v194, v127, 10, v194
	v_add_u32_e32 v195, 0x10000, v194
	v_lshrrev_b32_e32 v132, 5, v126
	v_lshl_add_u32 v133, v127, 1, v132
	v_and_b32_e32 v134, 31, v126
	v_xor_b32_e32 v134, v134, v133
	v_mul_u32_u24_e32 v196, 0x2c00, v133
	v_lshl_add_u32 v196, v134, 4, v196
	s_waitcnt lgkmcnt(0)
	s_barrier
	ds_read_b128 v[142:145], v194
	ds_read_b128 v[146:149], v194 offset:8192
	ds_read_b128 v[150:153], v194 offset:16384
	ds_read_b128 v[154:157], v194 offset:24576
	ds_read_b128 v[158:161], v194 offset:32768
	ds_read_b128 v[162:165], v194 offset:40960
	ds_read_b128 v[166:169], v194 offset:49152
	ds_read_b128 v[170:173], v194 offset:57344
	s_waitcnt lgkmcnt(7)
	global_store_dwordx4 v196, v[142:145], s[14:15]
	s_add_u32 s14, s14, 0x2c000
	s_addc_u32 s15, s15, 0
	s_nop 0
	ds_read_b128 v[142:145], v195
	s_waitcnt lgkmcnt(7)
	global_store_dwordx4 v196, v[146:149], s[14:15]
	s_add_u32 s14, s14, 0x2c000
	s_addc_u32 s15, s15, 0
	s_nop 0
	ds_read_b128 v[146:149], v195 offset:8192
	s_waitcnt lgkmcnt(7)
	global_store_dwordx4 v196, v[150:153], s[14:15]
	s_add_u32 s14, s14, 0x2c000
	s_addc_u32 s15, s15, 0
	s_nop 0
	ds_read_b128 v[150:153], v195 offset:16384
	s_waitcnt lgkmcnt(7)
	global_store_dwordx4 v196, v[154:157], s[14:15]
	s_add_u32 s14, s14, 0x2c000
	s_addc_u32 s15, s15, 0
	s_nop 0
	ds_read_b128 v[154:157], v195 offset:24576
	s_waitcnt lgkmcnt(7)
	global_store_dwordx4 v196, v[158:161], s[14:15]
	s_add_u32 s14, s14, 0x2c000
	s_addc_u32 s15, s15, 0
	s_nop 0
	ds_read_b128 v[158:161], v195 offset:32768
	s_waitcnt lgkmcnt(7)
	global_store_dwordx4 v196, v[162:165], s[14:15]
	s_add_u32 s14, s14, 0x2c000
	s_addc_u32 s15, s15, 0
	s_nop 0
	ds_read_b128 v[162:165], v195 offset:40960
	s_waitcnt lgkmcnt(7)
	global_store_dwordx4 v196, v[166:169], s[14:15]
	s_add_u32 s14, s14, 0x2c000
	s_addc_u32 s15, s15, 0
	s_nop 0
	ds_read_b128 v[166:169], v195 offset:49152
	s_waitcnt lgkmcnt(7)
	global_store_dwordx4 v196, v[170:173], s[14:15]
	s_add_u32 s14, s14, 0x2c000
	s_addc_u32 s15, s15, 0
	s_nop 0
	ds_read_b128 v[170:173], v195 offset:57344
	s_waitcnt lgkmcnt(7)
	global_store_dwordx4 v196, v[142:145], s[14:15]
	s_add_u32 s14, s14, 0x2c000
	s_addc_u32 s15, s15, 0
	s_waitcnt lgkmcnt(6)
	global_store_dwordx4 v196, v[146:149], s[14:15]
	s_add_u32 s14, s14, 0x2c000
	s_addc_u32 s15, s15, 0
	s_waitcnt lgkmcnt(5)
	global_store_dwordx4 v196, v[150:153], s[14:15]
	s_add_u32 s14, s14, 0x2c000
	s_addc_u32 s15, s15, 0
	s_waitcnt lgkmcnt(4)
	global_store_dwordx4 v196, v[154:157], s[14:15]
	s_add_u32 s14, s14, 0x2c000
	s_addc_u32 s15, s15, 0
	s_waitcnt lgkmcnt(3)
	global_store_dwordx4 v196, v[158:161], s[14:15]
	s_add_u32 s14, s14, 0x2c000
	s_addc_u32 s15, s15, 0
	s_waitcnt lgkmcnt(2)
	global_store_dwordx4 v196, v[162:165], s[14:15]
	s_add_u32 s14, s14, 0x2c000
	s_addc_u32 s15, s15, 0
	s_waitcnt lgkmcnt(1)
	global_store_dwordx4 v196, v[166:169], s[14:15]
	s_add_u32 s14, s14, 0x2c000
	s_addc_u32 s15, s15, 0
	s_waitcnt lgkmcnt(0)
	global_store_dwordx4 v196, v[170:173], s[14:15]
	v_readlane_b32 s36, v253, 33
	v_readlane_b32 s37, v253, 34
	v_readlane_b32 s38, v253, 35
	v_readlane_b32 s39, v253, 36
	v_readlane_b32 s40, v253, 37
	v_readlane_b32 s41, v253, 38
	v_readlane_b32 s42, v253, 39
	v_readlane_b32 s43, v253, 40
	v_readlane_b32 s44, v253, 41
	v_readlane_b32 s45, v253, 42
	v_readlane_b32 s46, v253, 43
	v_readlane_b32 s47, v253, 44
	v_readlane_b32 s48, v253, 45
	v_readlane_b32 s49, v253, 46
	v_readlane_b32 s50, v253, 47
	v_readlane_b32 s51, v253, 48
	s_add_i32 s76, s76, s96
	s_cmpk_gt_i32 s76, 0x3ff
	s_cbranch_scc1 .LBB0_69
	s_branch .LBB0_31
